# speedup vs baseline: 1.0256x; 1.0015x over previous
; template <int EPI, int PN>
; __device__ void gemm_phase(const Params& p, const u16* __restrict__ A, const u16* __restrict__ Bt, int nNt, char* smem) {
;     ...
;     for (int kt = 0; kt < 32; ++kt) {
;       asm volatile("s_waitcnt vmcnt(0)" ::: "memory");
;       __builtin_amdgcn_s_barrier();
;       const u16* Ab = ring + (kt & 1) * STG;
;       const u16* Bb = Ab + 16384;
;       u16* st = ring + ((kt + 1) & 1) * STG;
;       const bool pre = (kt + 1 < 32);
;       s16x8 af[2][4], bf[2][2];
;       auto ldfrag = [&](int ks, int slot) {
; #pragma unroll
;         for (int i = 0; i < 4; ++i) {
;           const int row = wr * 128 + i * 32 + lr;
;           af[slot][i] = *(const s16x8*)(Ab + row * 64 + (((ks * 2 + lh) ^ ((row >> 1) & 7)) * 8));
;         }
; #pragma unroll
;         for (int j = 0; j < 2; ++j) {
;           const int rowb = nh * 128 + wc * 64 + j * 32 + lr;
;           bf[slot][j] = *(const s16x8*)(Bb + rowb * 64 + (((ks * 2 + lh) ^ ((rowb >> 1) & 7)) * 8));
;         }
;       };
;       ldfrag(0, 0);
;       ldfrag(1, 1);
;       __builtin_amdgcn_sched_barrier(0);
; #pragma unroll
;       for (int ks = 0; ks < 4; ++ks) {
;         const int slot = ks & 1;
; #pragma unroll
;         for (int i = 0; i < 4; ++i) {
;           acc[i][0] = mfma32(af[slot][i], bf[slot][0], acc[i][0]);
;           acc[i][1] = mfma32(af[slot][i], bf[slot][1], acc[i][1]);
;           __builtin_amdgcn_sched_barrier(0);
;           if (pre && (i & 1) == 0) {
;             const int pi = ks * 2 + (i >> 1);
;             if (pi < 4) glds16(Ag0 + (size_t)pi * 64 * LDK + (kt + 1) * 64, st + (srow + 64 * pi) * 64 + sch * 8);
;             else glds16(Bg0 + (size_t)(pi - 4) * 64 * LDK + (kt + 1) * 64, st + 16384 + (srow + 64 * (pi - 4)) * 64 + sch * 8);
;             __builtin_amdgcn_sched_barrier(0);
;           }
;         }
;         if (ks + 2 < 4) { ldfrag(ks + 2, slot); __builtin_amdgcn_sched_barrier(0); }
;       }
.Lrot129_loop:
	s_add_i32 s13, s12, 0xffff8000
	s_and_b32 s13, s13, 0x8000
	s_lshl_b32 s13, s13, 1
	v_lshl_or_b32 v128, v143, 1, s13
	v_lshl_add_u32 v149, v147, 1, s13
	s_and_b32 s98, s12, 0x8000
	s_lshl_b32 s98, s98, 1
	s_waitcnt lgkmcnt(7)
	v_mfma_f32_32x32x16_bf16 v[64:79], v[178:181], v[194:197], v[64:79]
	v_add3_u32 v226, s98, v162, v156
	s_waitcnt lgkmcnt(6)
	v_mfma_f32_32x32x16_bf16 v[112:127], v[178:181], v[198:201], v[112:127]
	v_readfirstlane_b32 s100, v226
	s_mov_b32 s20, m0
	s_add_i32 m0, s100, 0x8000
	s_nop 0
	global_load_lds_dwordx4 v[160:161], off
	v_mfma_f32_32x32x16_bf16 v[32:47], v[182:185], v[194:197], v[32:47]
	v_lshl_add_u64 v[178:179], v[160:161], 0, s[2:3]
	s_add_i32 m0, s100, 0xa000
	s_nop 0
	global_load_lds_dwordx4 v[178:179], off
	v_mfma_f32_32x32x16_bf16 v[96:111], v[182:185], v[198:201], v[96:111]
	v_lshl_add_u64 v[180:181], v[160:161], 0, s[4:5]
	s_add_i32 m0, s100, 0xc000
	s_nop 0
	global_load_lds_dwordx4 v[180:181], off
	v_mfma_f32_32x32x16_bf16 v[16:31], v[186:189], v[194:197], v[16:31]
	v_lshl_add_u64 v[178:179], v[160:161], 0, s[6:7]
	s_add_i32 m0, s100, 0xe000
	s_nop 0
	global_load_lds_dwordx4 v[178:179], off
	s_mov_b32 m0, s20
	v_mfma_f32_32x32x16_bf16 v[80:95], v[186:189], v[198:201], v[80:95]
	v_mfma_f32_32x32x16_bf16 v[0:15], v[190:193], v[194:197], v[0:15]
	v_mfma_f32_32x32x16_bf16 v[48:63], v[190:193], v[198:201], v[48:63]
	v_lshl_add_u64 v[160:161], v[160:161], 0, s[8:9]
	v_add_u32_e32 v177, v128, v175
	ds_read_b128 v[178:181], v177
	ds_read_b128 v[182:185], v177 offset:4096
	ds_read_b128 v[186:189], v177 offset:8192
	ds_read_b128 v[190:193], v177 offset:12288
	v_add_u32_e32 v177, v149, v175
	ds_read_b128 v[194:197], v177 offset:32768
	ds_read_b128 v[198:201], v177 offset:36864
	s_waitcnt lgkmcnt(7)
	v_mfma_f32_32x32x16_bf16 v[64:79], v[202:205], v[218:221], v[64:79]
	s_waitcnt lgkmcnt(6)
	v_mfma_f32_32x32x16_bf16 v[112:127], v[202:205], v[222:225], v[112:127]
	v_mfma_f32_32x32x16_bf16 v[32:47], v[206:209], v[218:221], v[32:47]
	v_mfma_f32_32x32x16_bf16 v[96:111], v[206:209], v[222:225], v[96:111]
	v_mfma_f32_32x32x16_bf16 v[16:31], v[210:213], v[218:221], v[16:31]
	v_mfma_f32_32x32x16_bf16 v[80:95], v[210:213], v[222:225], v[80:95]
	v_mfma_f32_32x32x16_bf16 v[0:15], v[214:217], v[218:221], v[0:15]
	v_mfma_f32_32x32x16_bf16 v[48:63], v[214:217], v[222:225], v[48:63]
	v_add_u32_e32 v128, v128, v176
	ds_read_b128 v[202:205], v128
	ds_read_b128 v[206:209], v128 offset:4096
	ds_read_b128 v[210:213], v128 offset:8192
	ds_read_b128 v[214:217], v128 offset:12288
	v_add_u32_e32 v128, v149, v176
	ds_read_b128 v[218:221], v128 offset:32768
	ds_read_b128 v[222:225], v128 offset:36864
	s_waitcnt lgkmcnt(7)
	v_mfma_f32_32x32x16_bf16 v[64:79], v[178:181], v[194:197], v[64:79]
	s_waitcnt lgkmcnt(6)
	v_mfma_f32_32x32x16_bf16 v[112:127], v[178:181], v[198:201], v[112:127]
	v_mfma_f32_32x32x16_bf16 v[32:47], v[182:185], v[194:197], v[32:47]
	v_mfma_f32_32x32x16_bf16 v[96:111], v[182:185], v[198:201], v[96:111]
	v_mfma_f32_32x32x16_bf16 v[16:31], v[186:189], v[194:197], v[16:31]
	v_mfma_f32_32x32x16_bf16 v[80:95], v[186:189], v[198:201], v[80:95]
	v_mfma_f32_32x32x16_bf16 v[0:15], v[190:193], v[194:197], v[0:15]
	v_mfma_f32_32x32x16_bf16 v[48:63], v[190:193], v[198:201], v[48:63]
	v_lshl_or_b32 v227, v143, 1, s98
	v_lshl_add_u32 v229, v147, 1, s98
	v_add_u32_e32 v228, v227, v173
	v_add_u32_e32 v230, v229, v173
	s_waitcnt vmcnt(0) lgkmcnt(0)
	s_barrier
	ds_read_b128 v[178:181], v228
	ds_read_b128 v[182:185], v228 offset:4096
	ds_read_b128 v[186:189], v228 offset:8192
	ds_read_b128 v[190:193], v228 offset:12288
	ds_read_b128 v[194:197], v230 offset:32768
	ds_read_b128 v[198:201], v230 offset:36864
	v_add3_u32 v226, s13, v162, v156
	v_mfma_f32_32x32x16_bf16 v[64:79], v[202:205], v[218:221], v[64:79]
	v_readfirstlane_b32 s99, v226
	s_mov_b32 s20, m0
	s_mov_b32 m0, s99
	s_nop 0
	global_load_lds_dwordx4 v[158:159], off
	v_mfma_f32_32x32x16_bf16 v[112:127], v[202:205], v[222:225], v[112:127]
	v_lshl_add_u64 v[232:233], v[158:159], 0, s[2:3]
	s_add_i32 m0, s99, 0x2000
	s_nop 0
	global_load_lds_dwordx4 v[232:233], off
	v_mfma_f32_32x32x16_bf16 v[32:47], v[206:209], v[218:221], v[32:47]
	v_lshl_add_u64 v[234:235], v[158:159], 0, s[4:5]
	s_add_i32 m0, s99, 0x4000
	s_nop 0
	global_load_lds_dwordx4 v[234:235], off
	v_mfma_f32_32x32x16_bf16 v[96:111], v[206:209], v[222:225], v[96:111]
	v_lshl_add_u64 v[232:233], v[158:159], 0, s[6:7]
	s_add_i32 m0, s99, 0x6000
	s_nop 0
	global_load_lds_dwordx4 v[232:233], off
	s_mov_b32 m0, s20
	v_mfma_f32_32x32x16_bf16 v[16:31], v[210:213], v[218:221], v[16:31]
	v_mfma_f32_32x32x16_bf16 v[80:95], v[210:213], v[222:225], v[80:95]
	v_mfma_f32_32x32x16_bf16 v[0:15], v[214:217], v[218:221], v[0:15]
	v_mfma_f32_32x32x16_bf16 v[48:63], v[214:217], v[222:225], v[48:63]
	v_add_u32_e32 v228, v227, v174
	v_add_u32_e32 v230, v229, v174
	ds_read_b128 v[202:205], v228
	ds_read_b128 v[206:209], v228 offset:4096
	ds_read_b128 v[210:213], v228 offset:8192
	ds_read_b128 v[214:217], v228 offset:12288
	ds_read_b128 v[218:221], v230 offset:32768
	ds_read_b128 v[222:225], v230 offset:36864
	s_add_i32 s12, s12, 0x8000
	v_lshl_add_u64 v[158:159], v[158:159], 0, s[8:9]
	s_cmp_eq_u32 s12, 0xf8000
	s_cbranch_scc0 .Lrot129_loop
; template <int EPI, int PN>
; __device__ void gemm_phase(const Params& p, const u16* __restrict__ A, const u16* __restrict__ Bt, int nNt, char* smem) {
;     ...
;     for (int kt = 0; kt < 32; ++kt) {
;       asm volatile("s_waitcnt vmcnt(0)" ::: "memory");
;       __builtin_amdgcn_s_barrier();
;       const u16* Ab = ring + (kt & 1) * STG;
;       const u16* Bb = Ab + 16384;
;       u16* st = ring + ((kt + 1) & 1) * STG;
;       const bool pre = (kt + 1 < 32);
;       s16x8 af[2][4], bf[2][2];
;       auto ldfrag = [&](int ks, int slot) {
; #pragma unroll
;         for (int i = 0; i < 4; ++i) {
;           const int row = wr * 128 + i * 32 + lr;
;           af[slot][i] = *(const s16x8*)(Ab + row * 64 + (((ks * 2 + lh) ^ ((row >> 1) & 7)) * 8));
;         }
; #pragma unroll
;         for (int j = 0; j < 2; ++j) {
;           const int rowb = nh * 128 + wc * 64 + j * 32 + lr;
;           bf[slot][j] = *(const s16x8*)(Bb + rowb * 64 + (((ks * 2 + lh) ^ ((rowb >> 1) & 7)) * 8));
;         }
;       };
;       ldfrag(0, 0);
;       ldfrag(1, 1);
;       __builtin_amdgcn_sched_barrier(0);
; #pragma unroll
;       for (int ks = 0; ks < 4; ++ks) {
;         const int slot = ks & 1;
; #pragma unroll
;         for (int i = 0; i < 4; ++i) {
;           acc[i][0] = mfma32(af[slot][i], bf[slot][0], acc[i][0]);
;           acc[i][1] = mfma32(af[slot][i], bf[slot][1], acc[i][1]);
;           __builtin_amdgcn_sched_barrier(0);
;           if (pre && (i & 1) == 0) {
;             const int pi = ks * 2 + (i >> 1);
;             if (pi < 4) glds16(Ag0 + (size_t)pi * 64 * LDK + (kt + 1) * 64, st + (srow + 64 * pi) * 64 + sch * 8);
;             else glds16(Bg0 + (size_t)(pi - 4) * 64 * LDK + (kt + 1) * 64, st + 16384 + (srow + 64 * (pi - 4)) * 64 + sch * 8);
;             __builtin_amdgcn_sched_barrier(0);
;           }
;         }
;         if (ks + 2 < 4) { ldfrag(ks + 2, slot); __builtin_amdgcn_sched_barrier(0); }
;       }
	s_add_i32 s13, s12, 0xffff8000
	s_and_b32 s13, s13, 0x8000
	s_lshl_b32 s13, s13, 1
	v_lshl_or_b32 v128, v143, 1, s13
	v_lshl_add_u32 v149, v147, 1, s13
	s_and_b32 s98, s12, 0x8000
	s_lshl_b32 s98, s98, 1
	s_waitcnt lgkmcnt(7)
	v_mfma_f32_32x32x16_bf16 v[64:79], v[178:181], v[194:197], v[64:79]
	v_add3_u32 v226, s98, v162, v156
	s_waitcnt lgkmcnt(6)
	v_mfma_f32_32x32x16_bf16 v[112:127], v[178:181], v[198:201], v[112:127]
	v_readfirstlane_b32 s100, v226
	s_mov_b32 s20, m0
	s_add_i32 m0, s100, 0x8000
	s_nop 0
	global_load_lds_dwordx4 v[160:161], off
	v_mfma_f32_32x32x16_bf16 v[32:47], v[182:185], v[194:197], v[32:47]
	v_lshl_add_u64 v[178:179], v[160:161], 0, s[2:3]
	s_add_i32 m0, s100, 0xa000
	s_nop 0
	global_load_lds_dwordx4 v[178:179], off
	v_mfma_f32_32x32x16_bf16 v[96:111], v[182:185], v[198:201], v[96:111]
	v_lshl_add_u64 v[180:181], v[160:161], 0, s[4:5]
	s_add_i32 m0, s100, 0xc000
	s_nop 0
	global_load_lds_dwordx4 v[180:181], off
	v_mfma_f32_32x32x16_bf16 v[16:31], v[186:189], v[194:197], v[16:31]
	v_lshl_add_u64 v[178:179], v[160:161], 0, s[6:7]
	s_add_i32 m0, s100, 0xe000
	s_nop 0
	global_load_lds_dwordx4 v[178:179], off
	s_mov_b32 m0, s20
	v_mfma_f32_32x32x16_bf16 v[80:95], v[186:189], v[198:201], v[80:95]
	v_mfma_f32_32x32x16_bf16 v[0:15], v[190:193], v[194:197], v[0:15]
	v_mfma_f32_32x32x16_bf16 v[48:63], v[190:193], v[198:201], v[48:63]
	v_lshl_add_u64 v[160:161], v[160:161], 0, s[8:9]
	v_add_u32_e32 v177, v128, v175
	ds_read_b128 v[178:181], v177
	ds_read_b128 v[182:185], v177 offset:4096
	ds_read_b128 v[186:189], v177 offset:8192
	ds_read_b128 v[190:193], v177 offset:12288
	v_add_u32_e32 v177, v149, v175
	ds_read_b128 v[194:197], v177 offset:32768
	ds_read_b128 v[198:201], v177 offset:36864
	s_waitcnt lgkmcnt(7)
	v_mfma_f32_32x32x16_bf16 v[64:79], v[202:205], v[218:221], v[64:79]
	s_waitcnt lgkmcnt(6)
	v_mfma_f32_32x32x16_bf16 v[112:127], v[202:205], v[222:225], v[112:127]
	v_mfma_f32_32x32x16_bf16 v[32:47], v[206:209], v[218:221], v[32:47]
	v_mfma_f32_32x32x16_bf16 v[96:111], v[206:209], v[222:225], v[96:111]
	v_mfma_f32_32x32x16_bf16 v[16:31], v[210:213], v[218:221], v[16:31]
	v_mfma_f32_32x32x16_bf16 v[80:95], v[210:213], v[222:225], v[80:95]
	v_mfma_f32_32x32x16_bf16 v[0:15], v[214:217], v[218:221], v[0:15]
	v_mfma_f32_32x32x16_bf16 v[48:63], v[214:217], v[222:225], v[48:63]
	v_add_u32_e32 v128, v128, v176
	ds_read_b128 v[202:205], v128
	ds_read_b128 v[206:209], v128 offset:4096
	ds_read_b128 v[210:213], v128 offset:8192
	ds_read_b128 v[214:217], v128 offset:12288
	v_add_u32_e32 v128, v149, v176
	ds_read_b128 v[218:221], v128 offset:32768
	ds_read_b128 v[222:225], v128 offset:36864
	s_waitcnt lgkmcnt(7)
	v_mfma_f32_32x32x16_bf16 v[64:79], v[178:181], v[194:197], v[64:79]
	s_waitcnt lgkmcnt(6)
	v_mfma_f32_32x32x16_bf16 v[112:127], v[178:181], v[198:201], v[112:127]
	v_mfma_f32_32x32x16_bf16 v[32:47], v[182:185], v[194:197], v[32:47]
	v_mfma_f32_32x32x16_bf16 v[96:111], v[182:185], v[198:201], v[96:111]
	v_mfma_f32_32x32x16_bf16 v[16:31], v[186:189], v[194:197], v[16:31]
	v_mfma_f32_32x32x16_bf16 v[80:95], v[186:189], v[198:201], v[80:95]
	v_mfma_f32_32x32x16_bf16 v[0:15], v[190:193], v[194:197], v[0:15]
	v_mfma_f32_32x32x16_bf16 v[48:63], v[190:193], v[198:201], v[48:63]
	s_waitcnt lgkmcnt(1)
	v_mfma_f32_32x32x16_bf16 v[64:79], v[202:205], v[218:221], v[64:79]
	s_waitcnt lgkmcnt(0)
	v_mfma_f32_32x32x16_bf16 v[112:127], v[202:205], v[222:225], v[112:127]
	v_mfma_f32_32x32x16_bf16 v[32:47], v[206:209], v[218:221], v[32:47]
	v_mfma_f32_32x32x16_bf16 v[96:111], v[206:209], v[222:225], v[96:111]
	v_mfma_f32_32x32x16_bf16 v[16:31], v[210:213], v[218:221], v[16:31]
	v_mfma_f32_32x32x16_bf16 v[80:95], v[210:213], v[222:225], v[80:95]
	v_mfma_f32_32x32x16_bf16 v[0:15], v[214:217], v[218:221], v[0:15]
	v_mfma_f32_32x32x16_bf16 v[48:63], v[214:217], v[222:225], v[48:63]
	s_waitcnt vmcnt(0)
	s_barrier
	ds_read_b128 v[158:161], v164
	ds_read_b128 v[178:181], v164 offset:4096
	ds_read_b128 v[182:185], v164 offset:8192
	ds_read_b128 v[186:189], v164 offset:12288
	ds_read_b128 v[190:193], v165
	ds_read_b128 v[194:197], v165 offset:4096
	ds_read_b128 v[198:201], v166
	ds_read_b128 v[202:205], v166 offset:4096
	ds_read_b128 v[206:209], v166 offset:8192
	ds_read_b128 v[210:213], v166 offset:12288
	ds_read_b128 v[214:217], v168
	ds_read_b128 v[218:221], v168 offset:4096
	s_waitcnt lgkmcnt(7)
	v_mfma_f32_32x32x16_bf16 v[64:79], v[158:161], v[190:193], v[64:79]
	s_waitcnt lgkmcnt(6)
	v_mfma_f32_32x32x16_bf16 v[112:127], v[158:161], v[194:197], v[112:127]
	v_mfma_f32_32x32x16_bf16 v[32:47], v[178:181], v[190:193], v[32:47]
	v_mfma_f32_32x32x16_bf16 v[96:111], v[178:181], v[194:197], v[96:111]
	v_mfma_f32_32x32x16_bf16 v[16:31], v[182:185], v[190:193], v[16:31]
	v_mfma_f32_32x32x16_bf16 v[80:95], v[182:185], v[194:197], v[80:95]
	v_mfma_f32_32x32x16_bf16 v[0:15], v[186:189], v[190:193], v[0:15]
	v_mfma_f32_32x32x16_bf16 v[48:63], v[186:189], v[194:197], v[48:63]
	ds_read_b128 v[158:161], v169
	ds_read_b128 v[178:181], v169 offset:4096
	ds_read_b128 v[182:185], v169 offset:8192
	ds_read_b128 v[186:189], v169 offset:12288
	ds_read_b128 v[190:193], v170
	ds_read_b128 v[194:197], v170 offset:4096
	s_waitcnt lgkmcnt(7)
	v_mfma_f32_32x32x16_bf16 v[64:79], v[198:201], v[214:217], v[64:79]
	s_waitcnt lgkmcnt(6)
; __device__ __forceinline__ int accrow(int reg, int lh) { return (reg & 3) + 8 * (reg >> 2) + 4 * lh; }
; template <int EPI, int PN>
; __device__ void gemm_phase(const Params& p, const u16* __restrict__ A, const u16* __restrict__ Bt, int nNt, char* smem) {
;     ...
;     __syncthreads();
;     int mte = __builtin_amdgcn_readfirstlane(mt), nte = __builtin_amdgcn_readfirstlane(nt), lrE = lr, lhE = lh, laneE = lane;
;     asm volatile("" : "+s"(mte), "+s"(nte), "+v"(lrE), "+v"(lhE), "+v"(laneE));
;     unsigned char* et = (unsigned char*)smem + wv * 18432;
;     const int col0 = nte * 256 + nh * 128 + wc * 64;
;     const size_t row0 = (size_t)mte * 256 + wr * 128;
;     if (EPI == 1) {
; #pragma unroll
;       for (int j = 0; j < 2; ++j) {
; #pragma unroll
;         for (int i = 0; i < 4; ++i)
; #pragma unroll
;           for (int r = 0; r < 16; ++r) *(float*)(et + (i * 32 + accrow(r, lhE)) * 144 + lrE * 4) = acc[i][j][r];
; #pragma unroll
;         for (int it = 0; it < 16; ++it) {
;           const int c = it * 64 + laneE, row = c >> 3, seg = c & 7;
;           const float4 v = *(const float4*)(et + row * 144 + seg * 16);
;           const size_t g = (row0 + row) * DM + col0 + j * 32 + seg * 4;
;           const float4 xv = *(const float4*)(p.x + g);
;           const float4 hv = make_float4(xv.x + v.x, xv.y + v.y, xv.z + v.z, xv.w + v.w);
;           *(float4*)(p.out + g) = hv;
;           uint2 hb; hb.x = pack2(hv.x, hv.y); hb.y = pack2(hv.z, hv.w);
;           *(uint2*)(p.xn + (row0 + row) * LDK + col0 + j * 32 + seg * 4) = hb;
;         }
;       }
;     } else if (EPI == 0 && col0 >= NPROJ) {
; #pragma unroll
;       for (int i = 0; i < 4; ++i)
; #pragma unroll
;         for (int r = 0; r < 16; ++r) {
;           const size_t row = row0 + i * 32 + accrow(r, lhE);
;           const int col = col0 + lrE;
;           if (col < NIN) p.dtraw[row * 16 + (col - NPROJ)] = acc[i][0][r];
;         }
;     } else {
; #pragma unroll
;       for (int i = 0; i < 4; ++i)
; #pragma unroll
;         for (int j = 0; j < 2; ++j)
; #pragma unroll
;           for (int r = 0; r < 16; ++r) *(u16*)(et + (i * 32 + accrow(r, lhE)) * 144 + (j * 32 + lrE) * 2) = f2bf(acc[i][j][r]);
	v_mfma_f32_32x32x16_bf16 v[112:127], v[198:201], v[218:221], v[112:127]
	v_mfma_f32_32x32x16_bf16 v[32:47], v[202:205], v[214:217], v[32:47]
	v_mfma_f32_32x32x16_bf16 v[96:111], v[202:205], v[218:221], v[96:111]
	v_mfma_f32_32x32x16_bf16 v[16:31], v[206:209], v[214:217], v[16:31]
	v_mfma_f32_32x32x16_bf16 v[80:95], v[206:209], v[218:221], v[80:95]
	v_mfma_f32_32x32x16_bf16 v[0:15], v[210:213], v[214:217], v[0:15]
	v_mfma_f32_32x32x16_bf16 v[48:63], v[210:213], v[218:221], v[48:63]
	ds_read_b128 v[198:201], v171
	ds_read_b128 v[202:205], v171 offset:4096
	ds_read_b128 v[206:209], v171 offset:8192
	ds_read_b128 v[210:213], v171 offset:12288
	ds_read_b128 v[214:217], v172
	ds_read_b128 v[218:221], v172 offset:4096
	s_waitcnt lgkmcnt(7)
	v_mfma_f32_32x32x16_bf16 v[64:79], v[158:161], v[190:193], v[64:79]
	s_waitcnt lgkmcnt(6)
	v_mfma_f32_32x32x16_bf16 v[112:127], v[158:161], v[194:197], v[112:127]
	v_mfma_f32_32x32x16_bf16 v[32:47], v[178:181], v[190:193], v[32:47]
	v_mfma_f32_32x32x16_bf16 v[96:111], v[178:181], v[194:197], v[96:111]
	v_mfma_f32_32x32x16_bf16 v[16:31], v[182:185], v[190:193], v[16:31]
	v_mfma_f32_32x32x16_bf16 v[80:95], v[182:185], v[194:197], v[80:95]
	v_mfma_f32_32x32x16_bf16 v[0:15], v[186:189], v[190:193], v[0:15]
	v_mfma_f32_32x32x16_bf16 v[48:63], v[186:189], v[194:197], v[48:63]
	s_waitcnt lgkmcnt(1)
	v_mfma_f32_32x32x16_bf16 v[64:79], v[198:201], v[214:217], v[64:79]
	s_waitcnt lgkmcnt(0)
	v_mfma_f32_32x32x16_bf16 v[112:127], v[198:201], v[218:221], v[112:127]
	v_mfma_f32_32x32x16_bf16 v[32:47], v[202:205], v[214:217], v[32:47]
	v_mfma_f32_32x32x16_bf16 v[96:111], v[202:205], v[218:221], v[96:111]
	v_mfma_f32_32x32x16_bf16 v[16:31], v[206:209], v[214:217], v[16:31]
	v_mfma_f32_32x32x16_bf16 v[80:95], v[206:209], v[218:221], v[80:95]
	v_mfma_f32_32x32x16_bf16 v[0:15], v[210:213], v[214:217], v[0:15]
	v_mfma_f32_32x32x16_bf16 v[48:63], v[210:213], v[218:221], v[48:63]
	v_mov_b32_e32 v128, v139
	v_mov_b32_e32 v161, v137
	v_mov_b32_e32 v177, v135
	s_barrier
	s_nop 0
	v_lshl_add_u32 v160, s11, 8, v145
	s_ashr_i32 s11, s10, 31
	s_lshl_b64 s[10:11], s[10:11], 8
	v_mov_b32_e32 v159, s11
	v_or_b32_e32 v158, s10, v134
	v_cmp_gt_i32_e32 vcc, s14, v160
	s_and_saveexec_b64 s[10:11], vcc
	s_xor_b64 s[10:11], exec, s[10:11]
	s_cbranch_execz .LBB0_132
	v_lshlrev_b32_e32 v149, 1, v161
	v_mul_lo_u32 v128, v128, s15
	v_add3_u32 v128, v163, v149, v128
	v_cvt_pk_bf16_f32 v0, v0, s0
	v_cvt_pk_bf16_f32 v64, v64, s0
	v_cvt_pk_bf16_f32 v32, v32, s0
	v_cvt_pk_bf16_f32 v16, v16, s0
	ds_write_b16 v128, v0 offset:13824
	v_cvt_pk_bf16_f32 v0, v1, s0
	ds_write_b16 v128, v64
	v_cvt_pk_bf16_f32 v64, v65, s0
	ds_write_b16 v128, v32 offset:4608
	v_cvt_pk_bf16_f32 v32, v33, s0
	ds_write_b16 v128, v16 offset:9216
	v_cvt_pk_bf16_f32 v16, v17, s0
	ds_write_b16 v128, v0 offset:13968
	v_cvt_pk_bf16_f32 v0, v2, s0
	ds_write_b16 v128, v64 offset:144
	v_cvt_pk_bf16_f32 v64, v66, s0
	ds_write_b16 v128, v32 offset:4752
	v_cvt_pk_bf16_f32 v32, v34, s0
	ds_write_b16 v128, v16 offset:9360
	v_cvt_pk_bf16_f32 v16, v18, s0
	ds_write_b16 v128, v0 offset:14112
	v_cvt_pk_bf16_f32 v0, v3, s0
	ds_write_b16 v128, v64 offset:288
	v_cvt_pk_bf16_f32 v64, v67, s0
	ds_write_b16 v128, v32 offset:4896
	v_cvt_pk_bf16_f32 v32, v35, s0
	ds_write_b16 v128, v16 offset:9504
	v_cvt_pk_bf16_f32 v16, v19, s0
	ds_write_b16 v128, v0 offset:14256
	v_cvt_pk_bf16_f32 v0, v4, s0
	ds_write_b16 v128, v64 offset:432
	v_cvt_pk_bf16_f32 v64, v68, s0
	ds_write_b16 v128, v32 offset:5040
	v_cvt_pk_bf16_f32 v32, v36, s0
	ds_write_b16 v128, v16 offset:9648
	v_cvt_pk_bf16_f32 v16, v20, s0
	ds_write_b16 v128, v0 offset:14976
	v_cvt_pk_bf16_f32 v0, v5, s0
	ds_write_b16 v128, v64 offset:1152
	v_cvt_pk_bf16_f32 v64, v69, s0
	ds_write_b16 v128, v32 offset:5760
	v_cvt_pk_bf16_f32 v32, v37, s0
	ds_write_b16 v128, v16 offset:10368
	v_cvt_pk_bf16_f32 v16, v21, s0
	ds_write_b16 v128, v0 offset:15120
	v_cvt_pk_bf16_f32 v0, v6, s0
	ds_write_b16 v128, v64 offset:1296
	v_cvt_pk_bf16_f32 v64, v70, s0
	ds_write_b16 v128, v32 offset:5904
	v_cvt_pk_bf16_f32 v32, v38, s0
	ds_write_b16 v128, v16 offset:10512
	v_cvt_pk_bf16_f32 v16, v22, s0
	ds_write_b16 v128, v0 offset:15264
	v_cvt_pk_bf16_f32 v0, v7, s0
	ds_write_b16 v128, v64 offset:1440
	v_cvt_pk_bf16_f32 v64, v71, s0
	ds_write_b16 v128, v32 offset:6048
	v_cvt_pk_bf16_f32 v32, v39, s0
	ds_write_b16 v128, v16 offset:10656
	v_cvt_pk_bf16_f32 v16, v23, s0
	ds_write_b16 v128, v0 offset:15408
	v_cvt_pk_bf16_f32 v0, v8, s0
	ds_write_b16 v128, v64 offset:1584
	v_cvt_pk_bf16_f32 v64, v72, s0
	ds_write_b16 v128, v32 offset:6192
	v_cvt_pk_bf16_f32 v32, v40, s0
	ds_write_b16 v128, v16 offset:10800
	v_cvt_pk_bf16_f32 v16, v24, s0
	ds_write_b16 v128, v0 offset:16128
	v_cvt_pk_bf16_f32 v0, v9, s0
	ds_write_b16 v128, v64 offset:2304
	v_cvt_pk_bf16_f32 v64, v73, s0
	ds_write_b16 v128, v32 offset:6912
	v_cvt_pk_bf16_f32 v32, v41, s0
	ds_write_b16 v128, v16 offset:11520
	v_cvt_pk_bf16_f32 v16, v25, s0
	ds_write_b16 v128, v0 offset:16272
	v_cvt_pk_bf16_f32 v0, v10, s0
	ds_write_b16 v128, v64 offset:2448
	v_cvt_pk_bf16_f32 v64, v74, s0
	ds_write_b16 v128, v32 offset:7056
	v_cvt_pk_bf16_f32 v32, v42, s0
	ds_write_b16 v128, v16 offset:11664
	v_cvt_pk_bf16_f32 v16, v26, s0
	ds_write_b16 v128, v0 offset:16416
	v_cvt_pk_bf16_f32 v0, v11, s0
	ds_write_b16 v128, v64 offset:2592
	v_cvt_pk_bf16_f32 v64, v75, s0
	ds_write_b16 v128, v32 offset:7200
	v_cvt_pk_bf16_f32 v32, v43, s0
	ds_write_b16 v128, v16 offset:11808
	v_cvt_pk_bf16_f32 v16, v27, s0
	ds_write_b16 v128, v0 offset:16560
	v_cvt_pk_bf16_f32 v0, v12, s0
	ds_write_b16 v128, v64 offset:2736
	v_cvt_pk_bf16_f32 v64, v76, s0
; __device__ __forceinline__ int accrow(int reg, int lh) { return (reg & 3) + 8 * (reg >> 2) + 4 * lh; }
; template <int EPI, int PN>
; __device__ void gemm_phase(const Params& p, const u16* __restrict__ A, const u16* __restrict__ Bt, int nNt, char* smem) {
;     ...
;     } else {
; #pragma unroll
;       for (int i = 0; i < 4; ++i)
; #pragma unroll
;         for (int j = 0; j < 2; ++j)
; #pragma unroll
;           for (int r = 0; r < 16; ++r) *(u16*)(et + (i * 32 + accrow(r, lhE)) * 144 + (j * 32 + lrE) * 2) = f2bf(acc[i][j][r]);
; #pragma unroll
;       for (int it = 0; it < 16; ++it) {
;         const int c = it * 64 + laneE, row = c >> 3, seg = c & 7;
;         const uint4 v = *(const uint4*)(et + row * 144 + seg * 16);
;         if (EPI == 0) *(uint4*)(p.proj + (row0 + row) * NPROJ + col0 + seg * 8) = v;
;         else *(uint4*)(p.qp + (row0 + row) * DM + col0 + seg * 8) = v;
;       }
	ds_write_b16 v128, v32 offset:7344
	v_cvt_pk_bf16_f32 v32, v44, s0
	ds_write_b16 v128, v16 offset:11952
	v_cvt_pk_bf16_f32 v16, v28, s0
	ds_write_b16 v128, v0 offset:17280
	v_cvt_pk_bf16_f32 v0, v13, s0
	ds_write_b16 v128, v64 offset:3456
	v_cvt_pk_bf16_f32 v64, v77, s0
	ds_write_b16 v128, v32 offset:8064
	v_cvt_pk_bf16_f32 v32, v45, s0
	ds_write_b16 v128, v16 offset:12672
	v_cvt_pk_bf16_f32 v16, v29, s0
	ds_write_b16 v128, v0 offset:17424
	v_cvt_pk_bf16_f32 v0, v14, s0
	ds_write_b16 v128, v64 offset:3600
	v_cvt_pk_bf16_f32 v64, v78, s0
	ds_write_b16 v128, v32 offset:8208
	v_cvt_pk_bf16_f32 v32, v46, s0
	ds_write_b16 v128, v16 offset:12816
	v_cvt_pk_bf16_f32 v16, v30, s0
	ds_write_b16 v128, v0 offset:17568
	v_cvt_pk_bf16_f32 v0, v15, s0
	ds_write_b16 v128, v64 offset:3744
	v_cvt_pk_bf16_f32 v64, v79, s0
	ds_write_b16 v128, v32 offset:8352
	v_cvt_pk_bf16_f32 v32, v47, s0
	ds_write_b16 v128, v16 offset:12960
	v_cvt_pk_bf16_f32 v16, v31, s0
	ds_write_b16 v128, v0 offset:17712
	v_cvt_pk_bf16_f32 v0, v48, s0
	ds_write_b16 v128, v64 offset:3888
	v_cvt_pk_bf16_f32 v64, v112, s0
	ds_write_b16 v128, v32 offset:8496
	v_cvt_pk_bf16_f32 v32, v96, s0
	ds_write_b16 v128, v16 offset:13104
	v_cvt_pk_bf16_f32 v16, v80, s0
	ds_write_b16 v128, v0 offset:13888
	v_cvt_pk_bf16_f32 v0, v49, s0
	ds_write_b16 v128, v64 offset:64
	v_cvt_pk_bf16_f32 v64, v113, s0
	ds_write_b16 v128, v32 offset:4672
	v_cvt_pk_bf16_f32 v32, v97, s0
	ds_write_b16 v128, v16 offset:9280
	v_cvt_pk_bf16_f32 v16, v81, s0
	ds_write_b16 v128, v0 offset:14032
	v_cvt_pk_bf16_f32 v0, v50, s0
	ds_write_b16 v128, v64 offset:208
	v_cvt_pk_bf16_f32 v64, v114, s0
	ds_write_b16 v128, v32 offset:4816
	v_cvt_pk_bf16_f32 v32, v98, s0
	ds_write_b16 v128, v16 offset:9424
	v_cvt_pk_bf16_f32 v16, v82, s0
	ds_write_b16 v128, v0 offset:14176
	v_cvt_pk_bf16_f32 v0, v51, s0
	ds_write_b16 v128, v64 offset:352
	v_cvt_pk_bf16_f32 v64, v115, s0
	ds_write_b16 v128, v32 offset:4960
	v_cvt_pk_bf16_f32 v32, v99, s0
	ds_write_b16 v128, v16 offset:9568
	v_cvt_pk_bf16_f32 v16, v83, s0
	ds_write_b16 v128, v0 offset:14320
	v_cvt_pk_bf16_f32 v0, v52, s0
	ds_write_b16 v128, v64 offset:496
	v_cvt_pk_bf16_f32 v64, v116, s0
	ds_write_b16 v128, v32 offset:5104
	v_cvt_pk_bf16_f32 v32, v100, s0
	ds_write_b16 v128, v16 offset:9712
	v_cvt_pk_bf16_f32 v16, v84, s0
	ds_write_b16 v128, v0 offset:15040
	v_cvt_pk_bf16_f32 v0, v53, s0
	ds_write_b16 v128, v64 offset:1216
	v_cvt_pk_bf16_f32 v64, v117, s0
	ds_write_b16 v128, v32 offset:5824
	v_cvt_pk_bf16_f32 v32, v101, s0
	ds_write_b16 v128, v16 offset:10432
	v_cvt_pk_bf16_f32 v16, v85, s0
	ds_write_b16 v128, v0 offset:15184
	v_cvt_pk_bf16_f32 v0, v54, s0
	ds_write_b16 v128, v64 offset:1360
	v_cvt_pk_bf16_f32 v64, v118, s0
	ds_write_b16 v128, v32 offset:5968
	v_cvt_pk_bf16_f32 v32, v102, s0
	ds_write_b16 v128, v16 offset:10576
	v_cvt_pk_bf16_f32 v16, v86, s0
	ds_write_b16 v128, v0 offset:15328
	v_cvt_pk_bf16_f32 v0, v55, s0
	ds_write_b16 v128, v64 offset:1504
	v_cvt_pk_bf16_f32 v64, v119, s0
	ds_write_b16 v128, v32 offset:6112
	v_cvt_pk_bf16_f32 v32, v103, s0
	ds_write_b16 v128, v16 offset:10720
	v_cvt_pk_bf16_f32 v16, v87, s0
	ds_write_b16 v128, v0 offset:15472
	v_cvt_pk_bf16_f32 v0, v56, s0
	ds_write_b16 v128, v64 offset:1648
	v_cvt_pk_bf16_f32 v64, v120, s0
	ds_write_b16 v128, v32 offset:6256
	v_cvt_pk_bf16_f32 v32, v104, s0
	ds_write_b16 v128, v16 offset:10864
	v_cvt_pk_bf16_f32 v16, v88, s0
	ds_write_b16 v128, v0 offset:16192
	v_cvt_pk_bf16_f32 v0, v57, s0
	ds_write_b16 v128, v64 offset:2368
	v_cvt_pk_bf16_f32 v64, v121, s0
	ds_write_b16 v128, v32 offset:6976
	v_cvt_pk_bf16_f32 v32, v105, s0
	ds_write_b16 v128, v16 offset:11584
	v_cvt_pk_bf16_f32 v16, v89, s0
	ds_write_b16 v128, v0 offset:16336
	v_cvt_pk_bf16_f32 v0, v58, s0
	ds_write_b16 v128, v64 offset:2512
	v_cvt_pk_bf16_f32 v64, v122, s0
	ds_write_b16 v128, v32 offset:7120
	v_cvt_pk_bf16_f32 v32, v106, s0
	ds_write_b16 v128, v16 offset:11728
	v_cvt_pk_bf16_f32 v16, v90, s0
	ds_write_b16 v128, v0 offset:16480
	v_cvt_pk_bf16_f32 v0, v59, s0
	ds_write_b16 v128, v64 offset:2656
	v_cvt_pk_bf16_f32 v64, v123, s0
	ds_write_b16 v128, v32 offset:7264
	v_cvt_pk_bf16_f32 v32, v107, s0
	ds_write_b16 v128, v16 offset:11872
	v_cvt_pk_bf16_f32 v16, v91, s0
	ds_write_b16 v128, v0 offset:16624
	v_cvt_pk_bf16_f32 v0, v60, s0
	ds_write_b16 v128, v64 offset:2800
	v_cvt_pk_bf16_f32 v64, v124, s0
	ds_write_b16 v128, v32 offset:7408
	v_cvt_pk_bf16_f32 v32, v108, s0
	ds_write_b16 v128, v16 offset:12016
	v_cvt_pk_bf16_f32 v16, v92, s0
	ds_write_b16 v128, v0 offset:17344
	v_cvt_pk_bf16_f32 v0, v61, s0
	ds_write_b16 v128, v64 offset:3520
	v_cvt_pk_bf16_f32 v64, v125, s0
	ds_write_b16 v128, v32 offset:8128
	v_cvt_pk_bf16_f32 v32, v109, s0
	ds_write_b16 v128, v16 offset:12736
	v_cvt_pk_bf16_f32 v16, v93, s0
	ds_write_b16 v128, v0 offset:17488
	v_cvt_pk_bf16_f32 v0, v62, s0
	ds_write_b16 v128, v64 offset:3664
	v_cvt_pk_bf16_f32 v64, v126, s0
	ds_write_b16 v128, v32 offset:8272
	v_cvt_pk_bf16_f32 v32, v110, s0
	ds_write_b16 v128, v16 offset:12880
	v_cvt_pk_bf16_f32 v16, v94, s0
	ds_write_b16 v128, v0 offset:17632
	v_cvt_pk_bf16_f32 v0, v63, s0
	ds_write_b16 v128, v64 offset:3808
	v_cvt_pk_bf16_f32 v64, v127, s0
	ds_write_b16 v128, v32 offset:8416
	v_cvt_pk_bf16_f32 v32, v111, s0
	ds_write_b16 v128, v16 offset:13024
	v_cvt_pk_bf16_f32 v16, v95, s0
	ds_write_b16 v128, v0 offset:17776
	v_lshlrev_b32_e32 v0, 4, v177
	ds_write_b16 v128, v64 offset:3952
	ds_write_b16 v128, v32 offset:8560
	ds_write_b16 v128, v16 offset:13168
	v_and_b32_e32 v128, 0x70, v0
	v_add_u32_e32 v0, v163, v128
	v_ashrrev_i32_e32 v6, 3, v177
	v_readlane_b32 s36, v253, 39
	v_mad_u64_u32 v[2:3], s[12:13], v6, s16, v[0:1]
	v_ashrrev_i32_e32 v7, 31, v6
	v_readlane_b32 s40, v253, 43
	v_readlane_b32 s41, v253, 44
	ds_read_b128 v[2:5], v2
	v_lshl_add_u64 v[6:7], v[158:159], 0, v[6:7]
	v_mov_b64_e32 v[10:11], s[40:41]
	v_ashrrev_i32_e32 v161, 31, v160
	v_mad_u64_u32 v[8:9], s[12:13], v6, s17, v[10:11]
	v_mad_i32_i24 v9, v7, s17, v9
	v_lshlrev_b64 v[12:13], 1, v[160:161]
	v_add_u32_e32 v1, 64, v177
	v_lshl_add_u64 v[6:7], v[8:9], 0, v[12:13]
	v_ashrrev_i32_e32 v16, 3, v1
	v_lshl_add_u64 v[14:15], v[6:7], 0, v[128:129]
	v_mad_u64_u32 v[6:7], s[12:13], v16, s16, v[0:1]
	v_ashrrev_i32_e32 v17, 31, v16
	ds_read_b128 v[6:9], v6
	s_waitcnt lgkmcnt(1)
; template <int EPI, int PN>
; __device__ void gemm_phase(const Params& p, const u16* __restrict__ A, const u16* __restrict__ Bt, int nNt, char* smem) {
;     ...
; #pragma unroll
;       for (int it = 0; it < 16; ++it) {
;         const int c = it * 64 + laneE, row = c >> 3, seg = c & 7;
;         const uint4 v = *(const uint4*)(et + row * 144 + seg * 16);
;         if (EPI == 0) *(uint4*)(p.proj + (row0 + row) * NPROJ + col0 + seg * 8) = v;
;         else *(uint4*)(p.qp + (row0 + row) * DM + col0 + seg * 8) = v;
;       }
	global_store_dwordx4 v[14:15], v[2:5], off
	v_add_u32_e32 v1, 0x80, v177
	v_readlane_b32 s37, v253, 40
	v_lshl_add_u64 v[2:3], v[158:159], 0, v[16:17]
	v_mad_u64_u32 v[4:5], s[12:13], v2, s17, v[10:11]
	v_mad_i32_i24 v5, v3, s17, v5
	v_lshl_add_u64 v[2:3], v[4:5], 0, v[12:13]
	v_lshl_add_u64 v[2:3], v[2:3], 0, v[128:129]
	s_waitcnt lgkmcnt(0)
	global_store_dwordx4 v[2:3], v[6:9], off
	v_readlane_b32 s38, v253, 41
	v_readlane_b32 s39, v253, 42
	v_ashrrev_i32_e32 v6, 3, v1
	v_mad_u64_u32 v[2:3], s[12:13], v6, s16, v[0:1]
	v_ashrrev_i32_e32 v7, 31, v6
	ds_read_b128 v[2:5], v2
	v_lshl_add_u64 v[6:7], v[158:159], 0, v[6:7]
	v_mad_u64_u32 v[8:9], s[12:13], v6, s17, v[10:11]
	v_mad_i32_i24 v9, v7, s17, v9
	v_add_u32_e32 v1, 0xc0, v177
	v_lshl_add_u64 v[6:7], v[8:9], 0, v[12:13]
	v_ashrrev_i32_e32 v16, 3, v1
	v_lshl_add_u64 v[14:15], v[6:7], 0, v[128:129]
	v_mad_u64_u32 v[6:7], s[12:13], v16, s16, v[0:1]
	v_ashrrev_i32_e32 v17, 31, v16
	ds_read_b128 v[6:9], v6
	s_waitcnt lgkmcnt(1)
	global_store_dwordx4 v[14:15], v[2:5], off
	v_add_u32_e32 v1, 0x100, v177
	v_readlane_b32 s42, v253, 45
	v_lshl_add_u64 v[2:3], v[158:159], 0, v[16:17]
	v_mad_u64_u32 v[4:5], s[12:13], v2, s17, v[10:11]
	v_mad_i32_i24 v5, v3, s17, v5
	v_lshl_add_u64 v[2:3], v[4:5], 0, v[12:13]
	v_lshl_add_u64 v[2:3], v[2:3], 0, v[128:129]
	s_waitcnt lgkmcnt(0)
	global_store_dwordx4 v[2:3], v[6:9], off
	v_readlane_b32 s43, v253, 46
	v_readlane_b32 s44, v253, 47
	v_ashrrev_i32_e32 v6, 3, v1
	v_mad_u64_u32 v[2:3], s[12:13], v6, s16, v[0:1]
	v_ashrrev_i32_e32 v7, 31, v6
	ds_read_b128 v[2:5], v2
	v_lshl_add_u64 v[6:7], v[158:159], 0, v[6:7]
	v_mad_u64_u32 v[8:9], s[12:13], v6, s17, v[10:11]
	v_mad_i32_i24 v9, v7, s17, v9
	v_add_u32_e32 v1, 0x140, v177
	v_lshl_add_u64 v[6:7], v[8:9], 0, v[12:13]
	v_ashrrev_i32_e32 v16, 3, v1
	v_lshl_add_u64 v[14:15], v[6:7], 0, v[128:129]
	v_mad_u64_u32 v[6:7], s[12:13], v16, s16, v[0:1]
	v_ashrrev_i32_e32 v17, 31, v16
	ds_read_b128 v[6:9], v6
	s_waitcnt lgkmcnt(1)
	global_store_dwordx4 v[14:15], v[2:5], off
	v_add_u32_e32 v1, 0x180, v177
	v_readlane_b32 s45, v253, 48
	v_lshl_add_u64 v[2:3], v[158:159], 0, v[16:17]
	v_mad_u64_u32 v[4:5], s[12:13], v2, s17, v[10:11]
	v_mad_i32_i24 v5, v3, s17, v5
	v_lshl_add_u64 v[2:3], v[4:5], 0, v[12:13]
	v_lshl_add_u64 v[2:3], v[2:3], 0, v[128:129]
	s_waitcnt lgkmcnt(0)
	global_store_dwordx4 v[2:3], v[6:9], off
	v_readlane_b32 s46, v253, 49
	v_readlane_b32 s47, v253, 50
	v_ashrrev_i32_e32 v6, 3, v1
	v_mad_u64_u32 v[2:3], s[12:13], v6, s16, v[0:1]
	v_ashrrev_i32_e32 v7, 31, v6
	ds_read_b128 v[2:5], v2
	v_lshl_add_u64 v[6:7], v[158:159], 0, v[6:7]
	v_mad_u64_u32 v[8:9], s[12:13], v6, s17, v[10:11]
	v_mad_i32_i24 v9, v7, s17, v9
	v_add_u32_e32 v1, 0x1c0, v177
	v_lshl_add_u64 v[6:7], v[8:9], 0, v[12:13]
	v_ashrrev_i32_e32 v16, 3, v1
	v_lshl_add_u64 v[14:15], v[6:7], 0, v[128:129]
	v_mad_u64_u32 v[6:7], s[12:13], v16, s16, v[0:1]
	v_ashrrev_i32_e32 v17, 31, v16
	ds_read_b128 v[6:9], v6
	s_waitcnt lgkmcnt(1)
	global_store_dwordx4 v[14:15], v[2:5], off
	v_add_u32_e32 v1, 0x200, v177
	v_readlane_b32 s48, v253, 51
	v_lshl_add_u64 v[2:3], v[158:159], 0, v[16:17]
	v_mad_u64_u32 v[4:5], s[12:13], v2, s17, v[10:11]
	v_mad_i32_i24 v5, v3, s17, v5
	v_lshl_add_u64 v[2:3], v[4:5], 0, v[12:13]
	v_lshl_add_u64 v[2:3], v[2:3], 0, v[128:129]
	s_waitcnt lgkmcnt(0)
; template <int EPI, int PN>
; __device__ void gemm_phase(const Params& p, const u16* __restrict__ A, const u16* __restrict__ Bt, int nNt, char* smem) {
;     ...
; #pragma unroll
;       for (int it = 0; it < 16; ++it) {
;         const int c = it * 64 + laneE, row = c >> 3, seg = c & 7;
;         const uint4 v = *(const uint4*)(et + row * 144 + seg * 16);
;         if (EPI == 0) *(uint4*)(p.proj + (row0 + row) * NPROJ + col0 + seg * 8) = v;
;         else *(uint4*)(p.qp + (row0 + row) * DM + col0 + seg * 8) = v;
;       }
	global_store_dwordx4 v[2:3], v[6:9], off
	v_readlane_b32 s49, v253, 52
	v_readlane_b32 s50, v253, 53
	v_ashrrev_i32_e32 v6, 3, v1
	v_mad_u64_u32 v[2:3], s[12:13], v6, s16, v[0:1]
	v_ashrrev_i32_e32 v7, 31, v6
	ds_read_b128 v[2:5], v2
	v_lshl_add_u64 v[6:7], v[158:159], 0, v[6:7]
	v_mad_u64_u32 v[8:9], s[12:13], v6, s17, v[10:11]
	v_mad_i32_i24 v9, v7, s17, v9
	v_add_u32_e32 v1, 0x240, v177
	v_lshl_add_u64 v[6:7], v[8:9], 0, v[12:13]
	v_ashrrev_i32_e32 v16, 3, v1
	v_lshl_add_u64 v[14:15], v[6:7], 0, v[128:129]
	v_mad_u64_u32 v[6:7], s[12:13], v16, s16, v[0:1]
	v_ashrrev_i32_e32 v17, 31, v16
	ds_read_b128 v[6:9], v6
	s_waitcnt lgkmcnt(1)
	global_store_dwordx4 v[14:15], v[2:5], off
	v_add_u32_e32 v1, 0x280, v177
	v_readlane_b32 s51, v253, 54
	v_lshl_add_u64 v[2:3], v[158:159], 0, v[16:17]
	v_mad_u64_u32 v[4:5], s[12:13], v2, s17, v[10:11]
	v_mad_i32_i24 v5, v3, s17, v5
	v_lshl_add_u64 v[2:3], v[4:5], 0, v[12:13]
	v_lshl_add_u64 v[2:3], v[2:3], 0, v[128:129]
	s_waitcnt lgkmcnt(0)
	global_store_dwordx4 v[2:3], v[6:9], off
	s_nop 1
	v_ashrrev_i32_e32 v6, 3, v1
	v_mad_u64_u32 v[2:3], s[12:13], v6, s16, v[0:1]
	v_ashrrev_i32_e32 v7, 31, v6
	ds_read_b128 v[2:5], v2
	v_lshl_add_u64 v[6:7], v[158:159], 0, v[6:7]
	v_mad_u64_u32 v[8:9], s[12:13], v6, s17, v[10:11]
	v_mad_i32_i24 v9, v7, s17, v9
	v_add_u32_e32 v1, 0x2c0, v177
	v_lshl_add_u64 v[6:7], v[8:9], 0, v[12:13]
	v_ashrrev_i32_e32 v16, 3, v1
	v_lshl_add_u64 v[14:15], v[6:7], 0, v[128:129]
	v_mad_u64_u32 v[6:7], s[12:13], v16, s16, v[0:1]
	v_ashrrev_i32_e32 v17, 31, v16
	ds_read_b128 v[6:9], v6
	s_waitcnt lgkmcnt(1)
	global_store_dwordx4 v[14:15], v[2:5], off
	v_add_u32_e32 v1, 0x300, v177
	s_nop 0
	v_lshl_add_u64 v[2:3], v[158:159], 0, v[16:17]
	v_mad_u64_u32 v[4:5], s[12:13], v2, s17, v[10:11]
	v_mad_i32_i24 v5, v3, s17, v5
	v_lshl_add_u64 v[2:3], v[4:5], 0, v[12:13]
	v_lshl_add_u64 v[2:3], v[2:3], 0, v[128:129]
	s_waitcnt lgkmcnt(0)
	global_store_dwordx4 v[2:3], v[6:9], off
	s_nop 1
	v_ashrrev_i32_e32 v6, 3, v1
	v_mad_u64_u32 v[2:3], s[12:13], v6, s16, v[0:1]
	v_ashrrev_i32_e32 v7, 31, v6
	ds_read_b128 v[2:5], v2
	v_lshl_add_u64 v[6:7], v[158:159], 0, v[6:7]
	v_mad_u64_u32 v[8:9], s[12:13], v6, s17, v[10:11]
	v_mad_i32_i24 v9, v7, s17, v9
	v_add_u32_e32 v1, 0x340, v177
	v_lshl_add_u64 v[6:7], v[8:9], 0, v[12:13]
	v_ashrrev_i32_e32 v16, 3, v1
	v_lshl_add_u64 v[14:15], v[6:7], 0, v[128:129]
	v_mad_u64_u32 v[6:7], s[12:13], v16, s16, v[0:1]
	v_ashrrev_i32_e32 v17, 31, v16
	ds_read_b128 v[6:9], v6
	s_waitcnt lgkmcnt(1)
	global_store_dwordx4 v[14:15], v[2:5], off
	v_add_u32_e32 v1, 0x380, v177
	s_nop 0
	v_lshl_add_u64 v[2:3], v[158:159], 0, v[16:17]
	v_mad_u64_u32 v[4:5], s[12:13], v2, s17, v[10:11]
	v_mad_i32_i24 v5, v3, s17, v5
	v_lshl_add_u64 v[2:3], v[4:5], 0, v[12:13]
	v_lshl_add_u64 v[2:3], v[2:3], 0, v[128:129]
	s_waitcnt lgkmcnt(0)
	global_store_dwordx4 v[2:3], v[6:9], off
	s_nop 1
	v_ashrrev_i32_e32 v6, 3, v1
	v_mad_u64_u32 v[2:3], s[12:13], v6, s16, v[0:1]
	v_ashrrev_i32_e32 v7, 31, v6
	ds_read_b128 v[2:5], v2
	v_lshl_add_u64 v[6:7], v[158:159], 0, v[6:7]
	v_mad_u64_u32 v[8:9], s[12:13], v6, s17, v[10:11]
	v_add_u32_e32 v1, 0x3c0, v177
	v_mad_i32_i24 v9, v7, s17, v9
	v_ashrrev_i32_e32 v16, 3, v1
	v_lshl_add_u64 v[6:7], v[8:9], 0, v[12:13]
	v_mad_u64_u32 v[0:1], s[12:13], v16, s16, v[0:1]
	v_ashrrev_i32_e32 v17, 31, v16
	v_lshl_add_u64 v[14:15], v[6:7], 0, v[128:129]
	ds_read_b128 v[6:9], v0
	v_lshl_add_u64 v[0:1], v[158:159], 0, v[16:17]
	s_waitcnt lgkmcnt(1)
	global_store_dwordx4 v[14:15], v[2:5], off
	s_nop 1
	v_mad_u64_u32 v[2:3], s[12:13], v0, s17, v[10:11]
	v_mad_i32_i24 v3, v1, s17, v3
	v_lshl_add_u64 v[0:1], v[2:3], 0, v[12:13]
	v_lshl_add_u64 v[0:1], v[0:1], 0, v[128:129]
	s_waitcnt lgkmcnt(0)
	global_store_dwordx4 v[0:1], v[6:9], off

; template <int EPI, int PN>
; __device__ void gemm_phase(const Params& p, const u16* __restrict__ A, const u16* __restrict__ Bt, int nNt, char* smem) {
;     ...
;     for (int kt = 0; kt < 32; ++kt) {
;       asm volatile("s_waitcnt vmcnt(0)" ::: "memory");
;       __builtin_amdgcn_s_barrier();
;       const u16* Ab = ring + (kt & 1) * STG;
;       const u16* Bb = Ab + 16384;
;       u16* st = ring + ((kt + 1) & 1) * STG;
;       const bool pre = (kt + 1 < 32);
;       s16x8 af[2][4], bf[2][2];
;       auto ldfrag = [&](int ks, int slot) {
; #pragma unroll
;         for (int i = 0; i < 4; ++i) {
;           const int row = wr * 128 + i * 32 + lr;
;           af[slot][i] = *(const s16x8*)(Ab + row * 64 + (((ks * 2 + lh) ^ ((row >> 1) & 7)) * 8));
;         }
; #pragma unroll
;         for (int j = 0; j < 2; ++j) {
;           const int rowb = nh * 128 + wc * 64 + j * 32 + lr;
;           bf[slot][j] = *(const s16x8*)(Bb + rowb * 64 + (((ks * 2 + lh) ^ ((rowb >> 1) & 7)) * 8));
;         }
;       };
;       ldfrag(0, 0);
;       ldfrag(1, 1);
;       __builtin_amdgcn_sched_barrier(0);
; #pragma unroll
;       for (int ks = 0; ks < 4; ++ks) {
;         const int slot = ks & 1;
; #pragma unroll
;         for (int i = 0; i < 4; ++i) {
;           acc[i][0] = mfma32(af[slot][i], bf[slot][0], acc[i][0]);
;           acc[i][1] = mfma32(af[slot][i], bf[slot][1], acc[i][1]);
;           __builtin_amdgcn_sched_barrier(0);
;           if (pre && (i & 1) == 0) {
;             const int pi = ks * 2 + (i >> 1);
;             if (pi < 4) glds16(Ag0 + (size_t)pi * 64 * LDK + (kt + 1) * 64, st + (srow + 64 * pi) * 64 + sch * 8);
;             else glds16(Bg0 + (size_t)(pi - 4) * 64 * LDK + (kt + 1) * 64, st + 16384 + (srow + 64 * (pi - 4)) * 64 + sch * 8);
;             __builtin_amdgcn_sched_barrier(0);
;           }
;         }
;         if (ks + 2 < 4) { ldfrag(ks + 2, slot); __builtin_amdgcn_sched_barrier(0); }
;       }
.Lrot666_loop:
	s_add_i32 s18, s17, 0xffff8000
	s_and_b32 s18, s18, 0x8000
	s_lshl_b32 s18, s18, 1
	v_lshl_or_b32 v128, v143, 1, s18
	v_lshl_add_u32 v166, v147, 1, s18
	s_and_b32 s98, s17, 0x8000
	s_lshl_b32 s98, s98, 1
	s_waitcnt lgkmcnt(7)
	v_mfma_f32_32x32x16_bf16 v[112:127], v[162:165], v[180:183], v[112:127]
	v_add3_u32 v148, s98, v224, v156
	s_waitcnt lgkmcnt(6)
	v_mfma_f32_32x32x16_bf16 v[48:63], v[162:165], v[184:187], v[48:63]
	v_readfirstlane_b32 s100, v148
	s_mov_b32 s19, m0
	s_add_i32 m0, s100, 0x8000
	s_nop 0
	global_load_lds_dwordx4 v[160:161], off
	v_mfma_f32_32x32x16_bf16 v[96:111], v[168:171], v[180:183], v[96:111]
	v_lshl_add_u64 v[162:163], v[160:161], 0, s[4:5]
	s_add_i32 m0, s100, 0xa000
	s_nop 0
	global_load_lds_dwordx4 v[162:163], off
	v_mfma_f32_32x32x16_bf16 v[32:47], v[168:171], v[184:187], v[32:47]
	v_lshl_add_u64 v[164:165], v[160:161], 0, s[6:7]
	s_add_i32 m0, s100, 0xc000
	s_nop 0
	global_load_lds_dwordx4 v[164:165], off
	v_mfma_f32_32x32x16_bf16 v[80:95], v[172:175], v[180:183], v[80:95]
	v_lshl_add_u64 v[162:163], v[160:161], 0, s[8:9]
	s_add_i32 m0, s100, 0xe000
	s_nop 0
	global_load_lds_dwordx4 v[162:163], off
	s_mov_b32 m0, s19
	v_mfma_f32_32x32x16_bf16 v[16:31], v[172:175], v[184:187], v[16:31]
	v_mfma_f32_32x32x16_bf16 v[64:79], v[176:179], v[180:183], v[64:79]
	v_mfma_f32_32x32x16_bf16 v[0:15], v[176:179], v[184:187], v[0:15]
	v_lshl_add_u64 v[160:161], v[160:161], 0, s[10:11]
	v_add_u32_e32 v176, v128, v236
	ds_read_b128 v[162:165], v176
	ds_read_b128 v[168:171], v176 offset:4096
	ds_read_b128 v[172:175], v176 offset:8192
	ds_read_b128 v[176:179], v176 offset:12288
	v_add_u32_e32 v184, v166, v236
	ds_read_b128 v[180:183], v184 offset:32768
	ds_read_b128 v[184:187], v184 offset:36864
	s_waitcnt lgkmcnt(7)
	v_mfma_f32_32x32x16_bf16 v[112:127], v[188:191], v[204:207], v[112:127]
	s_waitcnt lgkmcnt(6)
	v_mfma_f32_32x32x16_bf16 v[48:63], v[188:191], v[208:211], v[48:63]
	v_mfma_f32_32x32x16_bf16 v[96:111], v[192:195], v[204:207], v[96:111]
	v_mfma_f32_32x32x16_bf16 v[32:47], v[192:195], v[208:211], v[32:47]
	v_mfma_f32_32x32x16_bf16 v[80:95], v[196:199], v[204:207], v[80:95]
	v_mfma_f32_32x32x16_bf16 v[16:31], v[196:199], v[208:211], v[16:31]
	v_mfma_f32_32x32x16_bf16 v[64:79], v[200:203], v[204:207], v[64:79]
	v_mfma_f32_32x32x16_bf16 v[0:15], v[200:203], v[208:211], v[0:15]
	v_add_u32_e32 v128, v128, v237
	ds_read_b128 v[188:191], v128
	ds_read_b128 v[192:195], v128 offset:4096
	ds_read_b128 v[196:199], v128 offset:8192
	ds_read_b128 v[200:203], v128 offset:12288
	v_add_u32_e32 v128, v166, v237
	ds_read_b128 v[204:207], v128 offset:32768
	ds_read_b128 v[208:211], v128 offset:36864
	s_waitcnt lgkmcnt(7)
	v_mfma_f32_32x32x16_bf16 v[112:127], v[162:165], v[180:183], v[112:127]
	s_waitcnt lgkmcnt(6)
	v_mfma_f32_32x32x16_bf16 v[48:63], v[162:165], v[184:187], v[48:63]
	v_mfma_f32_32x32x16_bf16 v[96:111], v[168:171], v[180:183], v[96:111]
	v_mfma_f32_32x32x16_bf16 v[32:47], v[168:171], v[184:187], v[32:47]
	v_mfma_f32_32x32x16_bf16 v[80:95], v[172:175], v[180:183], v[80:95]
	v_mfma_f32_32x32x16_bf16 v[16:31], v[172:175], v[184:187], v[16:31]
	v_mfma_f32_32x32x16_bf16 v[64:79], v[176:179], v[180:183], v[64:79]
	v_mfma_f32_32x32x16_bf16 v[0:15], v[176:179], v[184:187], v[0:15]
	v_lshl_or_b32 v212, v143, 1, s98
	v_lshl_add_u32 v213, v147, 1, s98
	v_add_u32_e32 v149, v212, v234
	v_add_u32_e32 v148, v213, v234
	s_waitcnt vmcnt(0) lgkmcnt(0)
	s_barrier
	ds_read_b128 v[162:165], v149
	ds_read_b128 v[168:171], v149 offset:4096
	ds_read_b128 v[172:175], v149 offset:8192
	ds_read_b128 v[176:179], v149 offset:12288
	ds_read_b128 v[180:183], v148 offset:32768
	ds_read_b128 v[184:187], v148 offset:36864
	v_add3_u32 v148, s18, v224, v156
	v_mfma_f32_32x32x16_bf16 v[112:127], v[188:191], v[204:207], v[112:127]
	v_readfirstlane_b32 s99, v148
	s_mov_b32 s19, m0
	s_mov_b32 m0, s99
	s_nop 0
	global_load_lds_dwordx4 v[158:159], off
	v_mfma_f32_32x32x16_bf16 v[48:63], v[188:191], v[208:211], v[48:63]
	v_lshl_add_u64 v[188:189], v[158:159], 0, s[4:5]
	s_add_i32 m0, s99, 0x2000
	s_nop 0
	global_load_lds_dwordx4 v[188:189], off
	v_mfma_f32_32x32x16_bf16 v[96:111], v[192:195], v[204:207], v[96:111]
	v_lshl_add_u64 v[190:191], v[158:159], 0, s[6:7]
	s_add_i32 m0, s99, 0x4000
	s_nop 0
	global_load_lds_dwordx4 v[190:191], off
	v_mfma_f32_32x32x16_bf16 v[32:47], v[192:195], v[208:211], v[32:47]
	v_lshl_add_u64 v[188:189], v[158:159], 0, s[8:9]
	s_add_i32 m0, s99, 0x6000
	s_nop 0
	global_load_lds_dwordx4 v[188:189], off
	s_mov_b32 m0, s19
	v_mfma_f32_32x32x16_bf16 v[80:95], v[196:199], v[204:207], v[80:95]
	v_mfma_f32_32x32x16_bf16 v[16:31], v[196:199], v[208:211], v[16:31]
	v_mfma_f32_32x32x16_bf16 v[64:79], v[200:203], v[204:207], v[64:79]
	v_mfma_f32_32x32x16_bf16 v[0:15], v[200:203], v[208:211], v[0:15]
	v_add_u32_e32 v149, v212, v235
	v_add_u32_e32 v148, v213, v235
	ds_read_b128 v[188:191], v149
	ds_read_b128 v[192:195], v149 offset:4096
	ds_read_b128 v[196:199], v149 offset:8192
	ds_read_b128 v[200:203], v149 offset:12288
	ds_read_b128 v[204:207], v148 offset:32768
	ds_read_b128 v[208:211], v148 offset:36864
	s_add_i32 s17, s17, 0x8000
	v_lshl_add_u64 v[158:159], v[158:159], 0, s[10:11]
	s_cmp_eq_u32 s17, 0xf8000
	s_cbranch_scc0 .Lrot666_loop
; template <int EPI, int PN>
; __device__ void gemm_phase(const Params& p, const u16* __restrict__ A, const u16* __restrict__ Bt, int nNt, char* smem) {
;     ...
;     for (int kt = 0; kt < 32; ++kt) {
;       asm volatile("s_waitcnt vmcnt(0)" ::: "memory");
;       __builtin_amdgcn_s_barrier();
;       const u16* Ab = ring + (kt & 1) * STG;
;       const u16* Bb = Ab + 16384;
;       u16* st = ring + ((kt + 1) & 1) * STG;
;       const bool pre = (kt + 1 < 32);
;       s16x8 af[2][4], bf[2][2];
;       auto ldfrag = [&](int ks, int slot) {
; #pragma unroll
;         for (int i = 0; i < 4; ++i) {
;           const int row = wr * 128 + i * 32 + lr;
;           af[slot][i] = *(const s16x8*)(Ab + row * 64 + (((ks * 2 + lh) ^ ((row >> 1) & 7)) * 8));
;         }
; #pragma unroll
;         for (int j = 0; j < 2; ++j) {
;           const int rowb = nh * 128 + wc * 64 + j * 32 + lr;
;           bf[slot][j] = *(const s16x8*)(Bb + rowb * 64 + (((ks * 2 + lh) ^ ((rowb >> 1) & 7)) * 8));
;         }
;       };
;       ldfrag(0, 0);
;       ldfrag(1, 1);
;       __builtin_amdgcn_sched_barrier(0);
; #pragma unroll
;       for (int ks = 0; ks < 4; ++ks) {
;         const int slot = ks & 1;
; #pragma unroll
;         for (int i = 0; i < 4; ++i) {
;           acc[i][0] = mfma32(af[slot][i], bf[slot][0], acc[i][0]);
;           acc[i][1] = mfma32(af[slot][i], bf[slot][1], acc[i][1]);
;           __builtin_amdgcn_sched_barrier(0);
;           if (pre && (i & 1) == 0) {
;             const int pi = ks * 2 + (i >> 1);
;             if (pi < 4) glds16(Ag0 + (size_t)pi * 64 * LDK + (kt + 1) * 64, st + (srow + 64 * pi) * 64 + sch * 8);
;             else glds16(Bg0 + (size_t)(pi - 4) * 64 * LDK + (kt + 1) * 64, st + 16384 + (srow + 64 * (pi - 4)) * 64 + sch * 8);
;             __builtin_amdgcn_sched_barrier(0);
;           }
;         }
;         if (ks + 2 < 4) { ldfrag(ks + 2, slot); __builtin_amdgcn_sched_barrier(0); }
;       }
	s_add_i32 s18, s17, 0xffff8000
	s_and_b32 s18, s18, 0x8000
	s_lshl_b32 s18, s18, 1
	v_lshl_or_b32 v128, v143, 1, s18
	v_lshl_add_u32 v166, v147, 1, s18
	s_and_b32 s98, s17, 0x8000
	s_lshl_b32 s98, s98, 1
	s_waitcnt lgkmcnt(7)
	v_mfma_f32_32x32x16_bf16 v[112:127], v[162:165], v[180:183], v[112:127]
	v_add3_u32 v148, s98, v224, v156
	s_waitcnt lgkmcnt(6)
	v_mfma_f32_32x32x16_bf16 v[48:63], v[162:165], v[184:187], v[48:63]
	v_readfirstlane_b32 s100, v148
	s_mov_b32 s19, m0
	s_add_i32 m0, s100, 0x8000
	s_nop 0
	global_load_lds_dwordx4 v[160:161], off
	v_mfma_f32_32x32x16_bf16 v[96:111], v[168:171], v[180:183], v[96:111]
	v_lshl_add_u64 v[162:163], v[160:161], 0, s[4:5]
	s_add_i32 m0, s100, 0xa000
	s_nop 0
	global_load_lds_dwordx4 v[162:163], off
	v_mfma_f32_32x32x16_bf16 v[32:47], v[168:171], v[184:187], v[32:47]
	v_lshl_add_u64 v[164:165], v[160:161], 0, s[6:7]
	s_add_i32 m0, s100, 0xc000
	s_nop 0
	global_load_lds_dwordx4 v[164:165], off
	v_mfma_f32_32x32x16_bf16 v[80:95], v[172:175], v[180:183], v[80:95]
	v_lshl_add_u64 v[162:163], v[160:161], 0, s[8:9]
	s_add_i32 m0, s100, 0xe000
	s_nop 0
	global_load_lds_dwordx4 v[162:163], off
	s_mov_b32 m0, s19
	v_mfma_f32_32x32x16_bf16 v[16:31], v[172:175], v[184:187], v[16:31]
	v_mfma_f32_32x32x16_bf16 v[64:79], v[176:179], v[180:183], v[64:79]
	v_mfma_f32_32x32x16_bf16 v[0:15], v[176:179], v[184:187], v[0:15]
	v_lshl_add_u64 v[160:161], v[160:161], 0, s[10:11]
	v_add_u32_e32 v176, v128, v236
	ds_read_b128 v[162:165], v176
	ds_read_b128 v[168:171], v176 offset:4096
	ds_read_b128 v[172:175], v176 offset:8192
	ds_read_b128 v[176:179], v176 offset:12288
	v_add_u32_e32 v184, v166, v236
	ds_read_b128 v[180:183], v184 offset:32768
	ds_read_b128 v[184:187], v184 offset:36864
	s_waitcnt lgkmcnt(7)
	v_mfma_f32_32x32x16_bf16 v[112:127], v[188:191], v[204:207], v[112:127]
	s_waitcnt lgkmcnt(6)
	v_mfma_f32_32x32x16_bf16 v[48:63], v[188:191], v[208:211], v[48:63]
	v_mfma_f32_32x32x16_bf16 v[96:111], v[192:195], v[204:207], v[96:111]
	v_mfma_f32_32x32x16_bf16 v[32:47], v[192:195], v[208:211], v[32:47]
	v_mfma_f32_32x32x16_bf16 v[80:95], v[196:199], v[204:207], v[80:95]
	v_mfma_f32_32x32x16_bf16 v[16:31], v[196:199], v[208:211], v[16:31]
	v_mfma_f32_32x32x16_bf16 v[64:79], v[200:203], v[204:207], v[64:79]
	v_mfma_f32_32x32x16_bf16 v[0:15], v[200:203], v[208:211], v[0:15]
	v_add_u32_e32 v128, v128, v237
	ds_read_b128 v[188:191], v128
	ds_read_b128 v[192:195], v128 offset:4096
	ds_read_b128 v[196:199], v128 offset:8192
	ds_read_b128 v[200:203], v128 offset:12288
	v_add_u32_e32 v128, v166, v237
	ds_read_b128 v[204:207], v128 offset:32768
	ds_read_b128 v[208:211], v128 offset:36864
	s_waitcnt lgkmcnt(7)
	v_mfma_f32_32x32x16_bf16 v[112:127], v[162:165], v[180:183], v[112:127]
	s_waitcnt lgkmcnt(6)
	v_mfma_f32_32x32x16_bf16 v[48:63], v[162:165], v[184:187], v[48:63]
	v_mfma_f32_32x32x16_bf16 v[96:111], v[168:171], v[180:183], v[96:111]
	v_mfma_f32_32x32x16_bf16 v[32:47], v[168:171], v[184:187], v[32:47]
	v_mfma_f32_32x32x16_bf16 v[80:95], v[172:175], v[180:183], v[80:95]
	v_mfma_f32_32x32x16_bf16 v[16:31], v[172:175], v[184:187], v[16:31]
	v_mfma_f32_32x32x16_bf16 v[64:79], v[176:179], v[180:183], v[64:79]
	v_mfma_f32_32x32x16_bf16 v[0:15], v[176:179], v[184:187], v[0:15]
	s_waitcnt lgkmcnt(1)
	v_mfma_f32_32x32x16_bf16 v[112:127], v[188:191], v[204:207], v[112:127]
	s_waitcnt lgkmcnt(0)
	v_mfma_f32_32x32x16_bf16 v[48:63], v[188:191], v[208:211], v[48:63]
	v_mfma_f32_32x32x16_bf16 v[96:111], v[192:195], v[204:207], v[96:111]
	v_mfma_f32_32x32x16_bf16 v[32:47], v[192:195], v[208:211], v[32:47]
	v_mfma_f32_32x32x16_bf16 v[80:95], v[196:199], v[204:207], v[80:95]
	v_mfma_f32_32x32x16_bf16 v[16:31], v[196:199], v[208:211], v[16:31]
	v_mfma_f32_32x32x16_bf16 v[64:79], v[200:203], v[204:207], v[64:79]
	v_mfma_f32_32x32x16_bf16 v[0:15], v[200:203], v[208:211], v[0:15]
	s_waitcnt vmcnt(0)
	s_barrier
	ds_read_b128 v[158:161], v226
	ds_read_b128 v[162:165], v226 offset:4096
	ds_read_b128 v[168:171], v226 offset:8192
	ds_read_b128 v[172:175], v226 offset:12288
	ds_read_b128 v[176:179], v227
	ds_read_b128 v[180:183], v227 offset:4096
	ds_read_b128 v[184:187], v228
	ds_read_b128 v[188:191], v228 offset:4096
	ds_read_b128 v[192:195], v228 offset:8192
	ds_read_b128 v[196:199], v228 offset:12288
	ds_read_b128 v[200:203], v229
	ds_read_b128 v[204:207], v229 offset:4096
	s_waitcnt lgkmcnt(7)
	v_mfma_f32_32x32x16_bf16 v[112:127], v[158:161], v[176:179], v[112:127]
	s_waitcnt lgkmcnt(6)
	v_mfma_f32_32x32x16_bf16 v[48:63], v[158:161], v[180:183], v[48:63]
	v_mfma_f32_32x32x16_bf16 v[96:111], v[162:165], v[176:179], v[96:111]
	v_mfma_f32_32x32x16_bf16 v[32:47], v[162:165], v[180:183], v[32:47]
	v_mfma_f32_32x32x16_bf16 v[80:95], v[168:171], v[176:179], v[80:95]
	v_mfma_f32_32x32x16_bf16 v[16:31], v[168:171], v[180:183], v[16:31]
	v_mfma_f32_32x32x16_bf16 v[64:79], v[172:175], v[176:179], v[64:79]
	v_mfma_f32_32x32x16_bf16 v[0:15], v[172:175], v[180:183], v[0:15]
	ds_read_b128 v[158:161], v230
	ds_read_b128 v[162:165], v230 offset:4096
	ds_read_b128 v[168:171], v230 offset:8192
	ds_read_b128 v[172:175], v230 offset:12288
	ds_read_b128 v[176:179], v231
	ds_read_b128 v[180:183], v231 offset:4096
	s_waitcnt lgkmcnt(7)
	v_mfma_f32_32x32x16_bf16 v[112:127], v[184:187], v[200:203], v[112:127]
	s_waitcnt lgkmcnt(6)
; __device__ __forceinline__ int accrow(int reg, int lh) { return (reg & 3) + 8 * (reg >> 2) + 4 * lh; }
; template <int EPI, int PN>
; __device__ void gemm_phase(const Params& p, const u16* __restrict__ A, const u16* __restrict__ Bt, int nNt, char* smem) {
;     ...
;     __syncthreads();
;     int mte = __builtin_amdgcn_readfirstlane(mt), nte = __builtin_amdgcn_readfirstlane(nt), lrE = lr, lhE = lh, laneE = lane;
;     asm volatile("" : "+s"(mte), "+s"(nte), "+v"(lrE), "+v"(lhE), "+v"(laneE));
;     unsigned char* et = (unsigned char*)smem + wv * 18432;
;     const int col0 = nte * 256 + nh * 128 + wc * 64;
;     const size_t row0 = (size_t)mte * 256 + wr * 128;
;     if (EPI == 1) {
; #pragma unroll
;       for (int j = 0; j < 2; ++j) {
; #pragma unroll
;         for (int i = 0; i < 4; ++i)
; #pragma unroll
;           for (int r = 0; r < 16; ++r) *(float*)(et + (i * 32 + accrow(r, lhE)) * 144 + lrE * 4) = acc[i][j][r];
; #pragma unroll
;         for (int it = 0; it < 16; ++it) {
;           const int c = it * 64 + laneE, row = c >> 3, seg = c & 7;
;           const float4 v = *(const float4*)(et + row * 144 + seg * 16);
;           const size_t g = (row0 + row) * DM + col0 + j * 32 + seg * 4;
;           const float4 xv = *(const float4*)(p.x + g);
	v_mfma_f32_32x32x16_bf16 v[48:63], v[184:187], v[204:207], v[48:63]
	v_mfma_f32_32x32x16_bf16 v[96:111], v[188:191], v[200:203], v[96:111]
	v_mfma_f32_32x32x16_bf16 v[32:47], v[188:191], v[204:207], v[32:47]
	v_mfma_f32_32x32x16_bf16 v[80:95], v[192:195], v[200:203], v[80:95]
	v_mfma_f32_32x32x16_bf16 v[16:31], v[192:195], v[204:207], v[16:31]
	v_mfma_f32_32x32x16_bf16 v[64:79], v[196:199], v[200:203], v[64:79]
	v_mfma_f32_32x32x16_bf16 v[0:15], v[196:199], v[204:207], v[0:15]
	ds_read_b128 v[184:187], v232
	ds_read_b128 v[188:191], v232 offset:4096
	ds_read_b128 v[192:195], v232 offset:8192
	ds_read_b128 v[196:199], v232 offset:12288
	ds_read_b128 v[200:203], v233
	ds_read_b128 v[204:207], v233 offset:4096
	s_waitcnt lgkmcnt(7)
	v_mfma_f32_32x32x16_bf16 v[112:127], v[158:161], v[176:179], v[112:127]
	s_waitcnt lgkmcnt(6)
	v_mfma_f32_32x32x16_bf16 v[48:63], v[158:161], v[180:183], v[48:63]
	v_mfma_f32_32x32x16_bf16 v[96:111], v[162:165], v[176:179], v[96:111]
	v_mfma_f32_32x32x16_bf16 v[32:47], v[162:165], v[180:183], v[32:47]
	v_mfma_f32_32x32x16_bf16 v[80:95], v[168:171], v[176:179], v[80:95]
	v_mfma_f32_32x32x16_bf16 v[16:31], v[168:171], v[180:183], v[16:31]
	v_mfma_f32_32x32x16_bf16 v[64:79], v[172:175], v[176:179], v[64:79]
	v_mfma_f32_32x32x16_bf16 v[0:15], v[172:175], v[180:183], v[0:15]
	s_waitcnt lgkmcnt(1)
	v_mfma_f32_32x32x16_bf16 v[112:127], v[184:187], v[200:203], v[112:127]
	s_waitcnt lgkmcnt(0)
	v_mfma_f32_32x32x16_bf16 v[48:63], v[184:187], v[204:207], v[48:63]
	v_mfma_f32_32x32x16_bf16 v[96:111], v[188:191], v[200:203], v[96:111]
	v_mfma_f32_32x32x16_bf16 v[32:47], v[188:191], v[204:207], v[32:47]
	v_mfma_f32_32x32x16_bf16 v[80:95], v[192:195], v[200:203], v[80:95]
	v_mfma_f32_32x32x16_bf16 v[16:31], v[192:195], v[204:207], v[16:31]
	v_mfma_f32_32x32x16_bf16 v[64:79], v[196:199], v[200:203], v[64:79]
	v_mfma_f32_32x32x16_bf16 v[0:15], v[196:199], v[204:207], v[0:15]
	v_mov_b32_e32 v128, v139
	v_mov_b32_e32 v148, v137
	v_mov_b32_e32 v218, v135
	s_barrier
	v_readlane_b32 s52, v253, 7
	v_lshl_add_u32 v172, s13, 8, v145
	s_ashr_i32 s13, s12, 31
	s_lshl_b64 s[12:13], s[12:13], 8
	v_ashrrev_i32_e32 v158, 3, v218
	v_mov_b32_e32 v163, s13
	v_or_b32_e32 v162, s12, v134
	v_ashrrev_i32_e32 v159, 31, v158
	v_and_b32_e32 v149, 7, v218
	v_ashrrev_i32_e32 v173, 31, v172
	v_lshl_add_u64 v[174:175], v[162:163], 0, v[158:159]
	v_lshl_or_b32 v164, v149, 2, v172
	v_mov_b32_e32 v165, v173
	v_lshlrev_b64 v[160:161], 11, v[174:175]
	v_lshl_add_u64 v[160:161], v[160:161], 0, v[164:165]
	v_lshlrev_b64 v[176:177], 2, v[160:161]
	v_readlane_b32 s53, v253, 8
	v_lshl_add_u32 v166, v149, 4, v225
	v_lshlrev_b32_e32 v148, 2, v148
	v_lshl_add_u64 v[160:161], s[52:53], 0, v[176:177]
	global_load_dwordx4 v[168:171], v[160:161], off
	v_mad_u64_u32 v[158:159], s[12:13], v158, s14, v[166:167]
	v_mul_lo_u32 v128, v128, s15
	v_add3_u32 v159, v225, v148, v128
	ds_write_b32 v159, v112
	ds_write_b32 v159, v113 offset:144
	ds_write_b32 v159, v114 offset:288
	ds_write_b32 v159, v115 offset:432
	ds_write_b32 v159, v116 offset:1152
	ds_write_b32 v159, v117 offset:1296
	ds_write_b32 v159, v118 offset:1440
	ds_write_b32 v159, v119 offset:1584
	ds_write_b32 v159, v120 offset:2304
	ds_write_b32 v159, v121 offset:2448
	ds_write_b32 v159, v122 offset:2592
	ds_write_b32 v159, v123 offset:2736
	ds_write_b32 v159, v124 offset:3456
	ds_write_b32 v159, v125 offset:3600
	ds_write_b32 v159, v126 offset:3744
	ds_write_b32 v159, v127 offset:3888
	ds_write_b32 v159, v96 offset:4608
	ds_write_b32 v159, v97 offset:4752
	ds_write_b32 v159, v98 offset:4896
	ds_write_b32 v159, v99 offset:5040
	ds_write_b32 v159, v100 offset:5760
	ds_write_b32 v159, v101 offset:5904
	ds_write_b32 v159, v102 offset:6048
	ds_write_b32 v159, v103 offset:6192
	ds_write_b32 v159, v104 offset:6912
	ds_write_b32 v159, v105 offset:7056
	ds_write_b32 v159, v106 offset:7200
	ds_write_b32 v159, v107 offset:7344
	ds_write_b32 v159, v108 offset:8064
	ds_write_b32 v159, v109 offset:8208
	ds_write_b32 v159, v110 offset:8352
	ds_write_b32 v159, v111 offset:8496
	ds_write_b32 v159, v80 offset:9216
	ds_write_b32 v159, v81 offset:9360
	ds_write_b32 v159, v82 offset:9504
	ds_write_b32 v159, v83 offset:9648
	ds_write_b32 v159, v84 offset:10368
	ds_write_b32 v159, v85 offset:10512
	ds_write_b32 v159, v86 offset:10656
	ds_write_b32 v159, v87 offset:10800
	ds_write_b32 v159, v88 offset:11520
	ds_write_b32 v159, v89 offset:11664
	ds_write_b32 v159, v90 offset:11808
	ds_write_b32 v159, v91 offset:11952
	ds_write_b32 v159, v92 offset:12672
	ds_write_b32 v159, v93 offset:12816
	ds_write_b32 v159, v94 offset:12960
	ds_write_b32 v159, v95 offset:13104
	ds_write_b32 v159, v64 offset:13824
	ds_write_b32 v159, v65 offset:13968
	ds_write_b32 v159, v66 offset:14112
	ds_write_b32 v159, v67 offset:14256
	ds_write_b32 v159, v68 offset:14976
	ds_write_b32 v159, v69 offset:15120
	ds_write_b32 v159, v70 offset:15264
	ds_write_b32 v159, v71 offset:15408
	ds_write_b32 v159, v72 offset:16128
	ds_write_b32 v159, v73 offset:16272
	ds_write_b32 v159, v74 offset:16416
	ds_write_b32 v159, v75 offset:16560
	ds_write_b32 v159, v76 offset:17280
	ds_write_b32 v159, v77 offset:17424
	ds_write_b32 v159, v78 offset:17568
	ds_write_b32 v159, v79 offset:17712
	ds_read_b128 v[66:69], v158
	v_readlane_b32 s36, v253, 23
	v_readlane_b32 s40, v253, 27
	v_readlane_b32 s41, v253, 28
	v_readlane_b32 s42, v253, 29
	v_readlane_b32 s43, v253, 30
	s_mov_b64 s[20:21], s[40:41]
	s_mov_b64 s[22:23], s[42:43]
	v_lshl_add_u64 v[64:65], s[20:21], 0, v[176:177]
	v_mov_b64_e32 v[102:103], s[22:23]
	v_lshlrev_b64 v[104:105], 1, v[172:173]
	v_lshlrev_b32_e32 v128, 3, v149
	v_readlane_b32 s54, v253, 9
	v_readlane_b32 s55, v253, 10
	v_readlane_b32 s56, v253, 11
	v_readlane_b32 s57, v253, 12
	v_readlane_b32 s58, v253, 13
	v_readlane_b32 s59, v253, 14
	v_readlane_b32 s60, v253, 15
	v_readlane_b32 s61, v253, 16
	v_readlane_b32 s62, v253, 17
	v_readlane_b32 s63, v253, 18
	v_readlane_b32 s64, v253, 19
	v_readlane_b32 s65, v253, 20
	v_readlane_b32 s66, v253, 21
	v_readlane_b32 s67, v253, 22
	v_readlane_b32 s37, v253, 24
	v_readlane_b32 s38, v253, 25
	v_readlane_b32 s39, v253, 26
	v_readlane_b32 s44, v253, 31
	v_readlane_b32 s45, v253, 32
	v_readlane_b32 s46, v253, 33
	v_readlane_b32 s47, v253, 34
	v_readlane_b32 s48, v253, 35
	v_readlane_b32 s49, v253, 36
	v_readlane_b32 s50, v253, 37
	v_readlane_b32 s51, v253, 38
	s_waitcnt vmcnt(0) lgkmcnt(0)
; template <int EPI, int PN>
; __device__ void gemm_phase(const Params& p, const u16* __restrict__ A, const u16* __restrict__ Bt, int nNt, char* smem) {
;     ...
; #pragma unroll
;         for (int it = 0; it < 16; ++it) {
;           const int c = it * 64 + laneE, row = c >> 3, seg = c & 7;
;           const float4 v = *(const float4*)(et + row * 144 + seg * 16);
;           const size_t g = (row0 + row) * DM + col0 + j * 32 + seg * 4;
;           const float4 xv = *(const float4*)(p.x + g);
;           const float4 hv = make_float4(xv.x + v.x, xv.y + v.y, xv.z + v.z, xv.w + v.w);
;           *(float4*)(p.out + g) = hv;
;           uint2 hb; hb.x = pack2(hv.x, hv.y); hb.y = pack2(hv.z, hv.w);
;           *(uint2*)(p.xn + (row0 + row) * LDK + col0 + j * 32 + seg * 4) = hb;
;         }
	v_pk_add_f32 v[66:67], v[66:67], v[168:169]
	v_pk_add_f32 v[68:69], v[68:69], v[170:171]
	global_store_dwordx4 v[64:65], v[66:69], off
	v_cvt_pk_bf16_f32 v70, v66, v67
	v_cvt_pk_bf16_f32 v71, v68, v69
	v_mad_u64_u32 v[66:67], s[12:13], v174, s2, v[102:103]
	v_mad_i32_i24 v67, v175, s2, v67
	v_lshl_add_u64 v[66:67], v[66:67], 0, v[104:105]
	v_lshl_add_u64 v[66:67], v[66:67], 0, v[128:129]
	v_add_u32_e32 v68, 64, v218
	global_store_dwordx2 v[66:67], v[70:71], off
	v_ashrrev_i32_e32 v70, 3, v68
	v_ashrrev_i32_e32 v71, 31, v70
	v_lshl_add_u64 v[74:75], v[162:163], 0, v[70:71]
	v_lshlrev_b64 v[68:69], 11, v[74:75]
	v_lshl_add_u64 v[68:69], v[68:69], 0, v[164:165]
	v_lshlrev_b64 v[76:77], 2, v[68:69]
	v_lshl_add_u64 v[68:69], s[52:53], 0, v[76:77]
	global_load_dwordx4 v[78:81], v[68:69], off
	v_mad_u64_u32 v[72:73], s[12:13], v70, s14, v[166:167]
	v_add_u32_e32 v71, 0x80, v218
	ds_read_b128 v[82:85], v72
	v_ashrrev_i32_e32 v90, 3, v71
	v_ashrrev_i32_e32 v91, 31, v90
	v_lshl_add_u64 v[94:95], v[162:163], 0, v[90:91]
	v_mad_u64_u32 v[70:71], s[12:13], v74, s2, v[102:103]
	v_lshlrev_b64 v[86:87], 11, v[94:95]
	v_mad_i32_i24 v71, v75, s2, v71
	v_lshl_add_u64 v[74:75], v[86:87], 0, v[164:165]
	v_lshl_add_u64 v[70:71], v[70:71], 0, v[104:105]
	v_lshl_add_u64 v[76:77], s[20:21], 0, v[76:77]
	v_lshlrev_b64 v[96:97], 2, v[74:75]
	v_lshl_add_u64 v[74:75], v[70:71], 0, v[128:129]
	v_lshl_add_u64 v[70:71], s[52:53], 0, v[96:97]
	v_add_u32_e32 v73, 0xc0, v218
	v_ashrrev_i32_e32 v98, 3, v73
	v_ashrrev_i32_e32 v99, 31, v98
	v_lshl_add_u64 v[106:107], v[162:163], 0, v[98:99]
	v_add_u32_e32 v73, 0x100, v218
	v_ashrrev_i32_e32 v110, 3, v73
	v_ashrrev_i32_e32 v111, 31, v110
	v_lshl_add_u64 v[114:115], v[162:163], 0, v[110:111]
	v_add_u32_e32 v73, 0x140, v218
	v_ashrrev_i32_e32 v118, 3, v73
	v_ashrrev_i32_e32 v119, 31, v118
	v_lshl_add_u64 v[122:123], v[162:163], 0, v[118:119]
	v_add_u32_e32 v73, 0x180, v218
	v_ashrrev_i32_e32 v126, 3, v73
	v_ashrrev_i32_e32 v127, 31, v126
	v_lshl_add_u64 v[172:173], v[162:163], 0, v[126:127]
	v_add_u32_e32 v73, 0x1c0, v218
	v_ashrrev_i32_e32 v176, 3, v73
	v_ashrrev_i32_e32 v177, 31, v176
	v_add_u32_e32 v73, 0x200, v218
	v_ashrrev_i32_e32 v182, 3, v73
	v_ashrrev_i32_e32 v183, 31, v182
	v_lshl_add_u64 v[186:187], v[162:163], 0, v[182:183]
	v_add_u32_e32 v73, 0x240, v218
	v_ashrrev_i32_e32 v190, 3, v73
	v_ashrrev_i32_e32 v191, 31, v190
	v_lshl_add_u64 v[194:195], v[162:163], 0, v[190:191]
	v_add_u32_e32 v73, 0x280, v218
	v_ashrrev_i32_e32 v198, 3, v73
	v_ashrrev_i32_e32 v199, 31, v198
	v_lshl_add_u64 v[202:203], v[162:163], 0, v[198:199]
	v_add_u32_e32 v73, 0x2c0, v218
	v_ashrrev_i32_e32 v206, 3, v73
	v_ashrrev_i32_e32 v207, 31, v206
	v_lshl_add_u64 v[210:211], v[162:163], 0, v[206:207]
	v_add_u32_e32 v73, 0x300, v218
	v_ashrrev_i32_e32 v214, 3, v73
	v_ashrrev_i32_e32 v215, 31, v214
	v_lshl_add_u64 v[220:221], v[162:163], 0, v[214:215]
	v_add_u32_e32 v73, 0x340, v218
	v_ashrrev_i32_e32 v238, 3, v73
	v_ashrrev_i32_e32 v239, 31, v238
	v_lshl_add_u64 v[242:243], v[162:163], 0, v[238:239]
	v_add_u32_e32 v73, 0x380, v218
	v_ashrrev_i32_e32 v246, 3, v73
	v_ashrrev_i32_e32 v247, 31, v246
	v_lshl_add_u64 v[248:249], v[162:163], 0, v[246:247]
	v_add_u32_e32 v73, 0x3c0, v218
	v_mad_u64_u32 v[218:219], s[12:13], v246, s14, v[166:167]
	v_ashrrev_i32_e32 v148, 3, v73
	v_ashrrev_i32_e32 v149, 31, v148
	v_lshl_add_u64 v[246:247], v[162:163], 0, v[148:149]
	s_waitcnt vmcnt(0) lgkmcnt(0)
	v_pk_add_f32 v[78:79], v[82:83], v[78:79]
	v_pk_add_f32 v[80:81], v[84:85], v[80:81]
	global_store_dwordx4 v[76:77], v[78:81], off
	v_lshlrev_b64 v[82:83], 11, v[106:107]
	v_lshl_add_u64 v[82:83], v[82:83], 0, v[164:165]
	v_cvt_pk_bf16_f32 v78, v78, v79
	v_cvt_pk_bf16_f32 v79, v80, v81
	global_store_dwordx2 v[74:75], v[78:79], off
	global_load_dwordx4 v[86:89], v[70:71], off
	v_mad_u64_u32 v[80:81], s[12:13], v90, s14, v[166:167]
	ds_read_b128 v[90:93], v80
	v_mad_u64_u32 v[78:79], s[12:13], v94, s2, v[102:103]
	v_mad_i32_i24 v79, v95, s2, v79
	v_lshl_add_u64 v[78:79], v[78:79], 0, v[104:105]
	v_lshl_add_u64 v[84:85], s[20:21], 0, v[96:97]
	v_lshlrev_b64 v[108:109], 2, v[82:83]
	v_lshl_add_u64 v[82:83], v[78:79], 0, v[128:129]
	v_lshl_add_u64 v[78:79], s[52:53], 0, v[108:109]
	s_waitcnt vmcnt(0) lgkmcnt(0)
	v_pk_add_f32 v[86:87], v[90:91], v[86:87]
	v_pk_add_f32 v[88:89], v[92:93], v[88:89]
	global_store_dwordx4 v[84:85], v[86:89], off
	v_lshlrev_b64 v[90:91], 11, v[114:115]
	v_lshl_add_u64 v[90:91], v[90:91], 0, v[164:165]
	v_cvt_pk_bf16_f32 v86, v86, v87
	v_cvt_pk_bf16_f32 v87, v88, v89
	global_store_dwordx2 v[82:83], v[86:87], off
	global_load_dwordx4 v[94:97], v[78:79], off
	v_mad_u64_u32 v[88:89], s[12:13], v98, s14, v[166:167]
	ds_read_b128 v[98:101], v88
	v_mad_u64_u32 v[86:87], s[12:13], v106, s2, v[102:103]
	v_mad_i32_i24 v87, v107, s2, v87
	v_lshl_add_u64 v[86:87], v[86:87], 0, v[104:105]
	v_lshl_add_u64 v[92:93], s[20:21], 0, v[108:109]
	v_lshlrev_b64 v[116:117], 2, v[90:91]
	v_lshl_add_u64 v[90:91], v[86:87], 0, v[128:129]
	v_lshl_add_u64 v[86:87], s[52:53], 0, v[116:117]
	s_waitcnt vmcnt(0) lgkmcnt(0)
	v_pk_add_f32 v[94:95], v[98:99], v[94:95]
	v_pk_add_f32 v[96:97], v[100:101], v[96:97]
	global_store_dwordx4 v[92:93], v[94:97], off
	v_lshlrev_b64 v[98:99], 11, v[122:123]
	v_lshl_add_u64 v[98:99], v[98:99], 0, v[164:165]
	v_cvt_pk_bf16_f32 v94, v94, v95
	v_cvt_pk_bf16_f32 v95, v96, v97
	global_store_dwordx2 v[90:91], v[94:95], off
	global_load_dwordx4 v[106:109], v[86:87], off
	v_mad_u64_u32 v[96:97], s[12:13], v110, s14, v[166:167]
	ds_read_b128 v[110:113], v96
	v_mad_u64_u32 v[94:95], s[12:13], v114, s2, v[102:103]
	v_mad_i32_i24 v95, v115, s2, v95
	v_lshl_add_u64 v[94:95], v[94:95], 0, v[104:105]
	v_lshl_add_u64 v[100:101], s[20:21], 0, v[116:117]
	v_lshlrev_b64 v[124:125], 2, v[98:99]
	v_lshl_add_u64 v[98:99], v[94:95], 0, v[128:129]
	v_lshl_add_u64 v[94:95], s[52:53], 0, v[124:125]
	s_waitcnt vmcnt(0) lgkmcnt(0)
; template <int EPI, int PN>
; __device__ void gemm_phase(const Params& p, const u16* __restrict__ A, const u16* __restrict__ Bt, int nNt, char* smem) {
;     ...
; #pragma unroll
;         for (int it = 0; it < 16; ++it) {
;           const int c = it * 64 + laneE, row = c >> 3, seg = c & 7;
;           const float4 v = *(const float4*)(et + row * 144 + seg * 16);
;           const size_t g = (row0 + row) * DM + col0 + j * 32 + seg * 4;
;           const float4 xv = *(const float4*)(p.x + g);
;           const float4 hv = make_float4(xv.x + v.x, xv.y + v.y, xv.z + v.z, xv.w + v.w);
;           *(float4*)(p.out + g) = hv;
;           uint2 hb; hb.x = pack2(hv.x, hv.y); hb.y = pack2(hv.z, hv.w);
;           *(uint2*)(p.xn + (row0 + row) * LDK + col0 + j * 32 + seg * 4) = hb;
;         }
	v_pk_add_f32 v[106:107], v[110:111], v[106:107]
	v_pk_add_f32 v[108:109], v[112:113], v[108:109]
	global_store_dwordx4 v[100:101], v[106:109], off
	v_lshlrev_b64 v[110:111], 11, v[172:173]
	v_lshl_add_u64 v[110:111], v[110:111], 0, v[164:165]
	v_cvt_pk_bf16_f32 v106, v106, v107
	v_cvt_pk_bf16_f32 v107, v108, v109
	global_store_dwordx2 v[98:99], v[106:107], off
	global_load_dwordx4 v[114:117], v[94:95], off
	v_mad_u64_u32 v[108:109], s[12:13], v118, s14, v[166:167]
	ds_read_b128 v[118:121], v108
	v_mad_u64_u32 v[106:107], s[12:13], v122, s2, v[102:103]
	v_mad_i32_i24 v107, v123, s2, v107
	v_lshl_add_u64 v[106:107], v[106:107], 0, v[104:105]
	v_lshl_add_u64 v[112:113], s[20:21], 0, v[124:125]
	v_lshlrev_b64 v[174:175], 2, v[110:111]
	v_lshl_add_u64 v[110:111], v[106:107], 0, v[128:129]
	v_lshl_add_u64 v[106:107], s[52:53], 0, v[174:175]
	s_waitcnt vmcnt(0) lgkmcnt(0)
	v_pk_add_f32 v[114:115], v[118:119], v[114:115]
	v_pk_add_f32 v[116:117], v[120:121], v[116:117]
	global_store_dwordx4 v[112:113], v[114:117], off
	v_lshl_add_u64 v[120:121], s[20:21], 0, v[174:175]
	s_nop 0
	v_cvt_pk_bf16_f32 v114, v114, v115
	v_cvt_pk_bf16_f32 v115, v116, v117
	global_store_dwordx2 v[110:111], v[114:115], off
	global_load_dwordx4 v[122:125], v[106:107], off
	v_mad_u64_u32 v[116:117], s[12:13], v126, s14, v[166:167]
	ds_read_b128 v[168:171], v116
	v_lshl_add_u64 v[126:127], v[162:163], 0, v[176:177]
	v_mad_u64_u32 v[114:115], s[12:13], v172, s2, v[102:103]
	v_lshlrev_b64 v[118:119], 11, v[126:127]
	v_mad_i32_i24 v115, v173, s2, v115
	v_lshl_add_u64 v[118:119], v[118:119], 0, v[164:165]
	v_lshl_add_u64 v[114:115], v[114:115], 0, v[104:105]
	v_lshlrev_b64 v[178:179], 2, v[118:119]
	v_lshl_add_u64 v[118:119], v[114:115], 0, v[128:129]
	v_lshl_add_u64 v[114:115], s[52:53], 0, v[178:179]
	v_mad_u64_u32 v[162:163], s[12:13], v248, s2, v[102:103]
	v_mad_i32_i24 v163, v249, s2, v163
	v_lshl_add_u64 v[162:163], v[162:163], 0, v[104:105]
	s_waitcnt vmcnt(0) lgkmcnt(0)
	v_pk_add_f32 v[122:123], v[168:169], v[122:123]
	v_pk_add_f32 v[124:125], v[170:171], v[124:125]
	global_store_dwordx4 v[120:121], v[122:125], off
	v_lshlrev_b64 v[168:169], 11, v[186:187]
	s_nop 0
	v_cvt_pk_bf16_f32 v122, v122, v123
	v_cvt_pk_bf16_f32 v123, v124, v125
	global_store_dwordx2 v[118:119], v[122:123], off
	global_load_dwordx4 v[170:173], v[114:115], off
	v_mad_u64_u32 v[124:125], s[12:13], v176, s14, v[166:167]
	ds_read_b128 v[174:177], v124
	v_mad_u64_u32 v[122:123], s[12:13], v126, s2, v[102:103]
	v_mad_i32_i24 v123, v127, s2, v123
	v_lshl_add_u64 v[126:127], v[168:169], 0, v[164:165]
	v_lshl_add_u64 v[122:123], v[122:123], 0, v[104:105]
	v_lshl_add_u64 v[168:169], s[20:21], 0, v[178:179]
	v_lshlrev_b64 v[188:189], 2, v[126:127]
	v_lshl_add_u64 v[126:127], v[122:123], 0, v[128:129]
	v_lshl_add_u64 v[122:123], s[52:53], 0, v[188:189]
	s_waitcnt vmcnt(0) lgkmcnt(0)
	v_pk_add_f32 v[170:171], v[174:175], v[170:171]
	v_pk_add_f32 v[172:173], v[176:177], v[172:173]
	global_store_dwordx4 v[168:169], v[170:173], off
	v_lshlrev_b64 v[174:175], 11, v[194:195]
	v_lshl_add_u64 v[174:175], v[174:175], 0, v[164:165]
	v_cvt_pk_bf16_f32 v170, v170, v171
	v_cvt_pk_bf16_f32 v171, v172, v173
	global_store_dwordx2 v[126:127], v[170:171], off
	global_load_dwordx4 v[178:181], v[122:123], off
	v_mad_u64_u32 v[172:173], s[12:13], v182, s14, v[166:167]
	ds_read_b128 v[182:185], v172
	v_mad_u64_u32 v[170:171], s[12:13], v186, s2, v[102:103]
	v_mad_i32_i24 v171, v187, s2, v171
	v_lshl_add_u64 v[170:171], v[170:171], 0, v[104:105]
	v_lshl_add_u64 v[176:177], s[20:21], 0, v[188:189]
	v_lshlrev_b64 v[196:197], 2, v[174:175]
	v_lshl_add_u64 v[174:175], v[170:171], 0, v[128:129]
	v_lshl_add_u64 v[170:171], s[52:53], 0, v[196:197]
	s_waitcnt vmcnt(0) lgkmcnt(0)
	v_pk_add_f32 v[178:179], v[182:183], v[178:179]
	v_pk_add_f32 v[180:181], v[184:185], v[180:181]
	global_store_dwordx4 v[176:177], v[178:181], off
	v_lshlrev_b64 v[182:183], 11, v[202:203]
	v_lshl_add_u64 v[182:183], v[182:183], 0, v[164:165]
	v_cvt_pk_bf16_f32 v178, v178, v179
	v_cvt_pk_bf16_f32 v179, v180, v181
	global_store_dwordx2 v[174:175], v[178:179], off
	global_load_dwordx4 v[186:189], v[170:171], off
	v_mad_u64_u32 v[180:181], s[12:13], v190, s14, v[166:167]
	ds_read_b128 v[190:193], v180
	v_mad_u64_u32 v[178:179], s[12:13], v194, s2, v[102:103]
	v_mad_i32_i24 v179, v195, s2, v179
	v_lshl_add_u64 v[178:179], v[178:179], 0, v[104:105]
	v_lshl_add_u64 v[184:185], s[20:21], 0, v[196:197]
	v_lshlrev_b64 v[204:205], 2, v[182:183]
	v_lshl_add_u64 v[182:183], v[178:179], 0, v[128:129]
	v_lshl_add_u64 v[178:179], s[52:53], 0, v[204:205]
	s_waitcnt vmcnt(0) lgkmcnt(0)
	v_pk_add_f32 v[186:187], v[190:191], v[186:187]
	v_pk_add_f32 v[188:189], v[192:193], v[188:189]
	global_store_dwordx4 v[184:185], v[186:189], off
	v_lshlrev_b64 v[190:191], 11, v[210:211]
	v_lshl_add_u64 v[190:191], v[190:191], 0, v[164:165]
	v_cvt_pk_bf16_f32 v186, v186, v187
	v_cvt_pk_bf16_f32 v187, v188, v189
	global_store_dwordx2 v[182:183], v[186:187], off
	global_load_dwordx4 v[194:197], v[178:179], off
	v_mad_u64_u32 v[188:189], s[12:13], v198, s14, v[166:167]
	ds_read_b128 v[198:201], v188
	v_mad_u64_u32 v[186:187], s[12:13], v202, s2, v[102:103]
	v_mad_i32_i24 v187, v203, s2, v187
	v_lshl_add_u64 v[186:187], v[186:187], 0, v[104:105]
	v_lshl_add_u64 v[192:193], s[20:21], 0, v[204:205]
	v_lshlrev_b64 v[212:213], 2, v[190:191]
	v_lshl_add_u64 v[190:191], v[186:187], 0, v[128:129]
	v_lshl_add_u64 v[186:187], s[52:53], 0, v[212:213]
	s_waitcnt vmcnt(0) lgkmcnt(0)
; template <int EPI, int PN>
; __device__ void gemm_phase(const Params& p, const u16* __restrict__ A, const u16* __restrict__ Bt, int nNt, char* smem) {
;     ...
;   for (int q = jb;; q += NJ) {
;     const int pl = q / (4 * PN), w = q % (4 * PN);
;     const int gp = pl * 8 + xcd;
;     if (gp >= npatch) break;
;     ...
; #pragma unroll
;         for (int it = 0; it < 16; ++it) {
;           const int c = it * 64 + laneE, row = c >> 3, seg = c & 7;
;           const float4 v = *(const float4*)(et + row * 144 + seg * 16);
;           const size_t g = (row0 + row) * DM + col0 + j * 32 + seg * 4;
;           const float4 xv = *(const float4*)(p.x + g);
;           const float4 hv = make_float4(xv.x + v.x, xv.y + v.y, xv.z + v.z, xv.w + v.w);
;           *(float4*)(p.out + g) = hv;
;           uint2 hb; hb.x = pack2(hv.x, hv.y); hb.y = pack2(hv.z, hv.w);
;           *(uint2*)(p.xn + (row0 + row) * LDK + col0 + j * 32 + seg * 4) = hb;
;         }
	v_pk_add_f32 v[194:195], v[198:199], v[194:195]
	v_pk_add_f32 v[196:197], v[200:201], v[196:197]
	global_store_dwordx4 v[192:193], v[194:197], off
	v_lshlrev_b64 v[198:199], 11, v[220:221]
	v_lshl_add_u64 v[198:199], v[198:199], 0, v[164:165]
	v_cvt_pk_bf16_f32 v194, v194, v195
	v_cvt_pk_bf16_f32 v195, v196, v197
	global_store_dwordx2 v[190:191], v[194:195], off
	global_load_dwordx4 v[202:205], v[186:187], off
	v_mad_u64_u32 v[196:197], s[12:13], v206, s14, v[166:167]
	ds_read_b128 v[206:209], v196
	v_mad_u64_u32 v[194:195], s[12:13], v210, s2, v[102:103]
	v_mad_i32_i24 v195, v211, s2, v195
	v_lshl_add_u64 v[194:195], v[194:195], 0, v[104:105]
	v_lshl_add_u64 v[200:201], s[20:21], 0, v[212:213]
	v_lshlrev_b64 v[222:223], 2, v[198:199]
	v_lshl_add_u64 v[198:199], v[194:195], 0, v[128:129]
	v_lshl_add_u64 v[194:195], s[52:53], 0, v[222:223]
	s_waitcnt vmcnt(0) lgkmcnt(0)
	v_pk_add_f32 v[202:203], v[206:207], v[202:203]
	v_pk_add_f32 v[204:205], v[208:209], v[204:205]
	global_store_dwordx4 v[200:201], v[202:205], off
	v_lshlrev_b64 v[206:207], 11, v[242:243]
	v_lshl_add_u64 v[206:207], v[206:207], 0, v[164:165]
	v_cvt_pk_bf16_f32 v202, v202, v203
	v_cvt_pk_bf16_f32 v203, v204, v205
	global_store_dwordx2 v[198:199], v[202:203], off
	global_load_dwordx4 v[210:213], v[194:195], off
	v_mad_u64_u32 v[204:205], s[12:13], v214, s14, v[166:167]
	ds_read_b128 v[214:217], v204
	v_mad_u64_u32 v[202:203], s[12:13], v220, s2, v[102:103]
	v_mad_i32_i24 v203, v221, s2, v203
	v_lshl_add_u64 v[202:203], v[202:203], 0, v[104:105]
	v_lshl_add_u64 v[208:209], s[20:21], 0, v[222:223]
	v_lshlrev_b64 v[244:245], 2, v[206:207]
	v_lshl_add_u64 v[206:207], v[202:203], 0, v[128:129]
	v_lshl_add_u64 v[202:203], s[52:53], 0, v[244:245]
	s_waitcnt vmcnt(0) lgkmcnt(0)
	v_pk_add_f32 v[210:211], v[214:215], v[210:211]
	v_pk_add_f32 v[212:213], v[216:217], v[212:213]
	global_store_dwordx4 v[208:209], v[210:213], off
	v_lshlrev_b64 v[214:215], 11, v[248:249]
	v_lshl_add_u64 v[214:215], v[214:215], 0, v[164:165]
	v_cvt_pk_bf16_f32 v210, v210, v211
	v_cvt_pk_bf16_f32 v211, v212, v213
	global_store_dwordx2 v[206:207], v[210:211], off
	global_load_dwordx4 v[220:223], v[202:203], off
	v_mad_u64_u32 v[212:213], s[12:13], v238, s14, v[166:167]
	ds_read_b128 v[238:241], v212
	v_mad_u64_u32 v[210:211], s[12:13], v242, s2, v[102:103]
	v_mad_i32_i24 v211, v243, s2, v211
	v_lshl_add_u64 v[210:211], v[210:211], 0, v[104:105]
	v_lshl_add_u64 v[216:217], s[20:21], 0, v[244:245]
	ds_read_b128 v[242:245], v218
	v_lshlrev_b64 v[250:251], 2, v[214:215]
	v_lshl_add_u64 v[214:215], v[210:211], 0, v[128:129]
	v_lshl_add_u64 v[210:211], s[52:53], 0, v[250:251]
	v_mad_u64_u32 v[102:103], s[12:13], v246, s2, v[102:103]
	v_mad_i32_i24 v103, v247, s2, v103
	v_lshl_add_u64 v[102:103], v[102:103], 0, v[104:105]
	v_lshl_add_u64 v[102:103], v[102:103], 0, v[128:129]
	s_waitcnt vmcnt(0) lgkmcnt(1)
	v_pk_add_f32 v[220:221], v[238:239], v[220:221]
	v_pk_add_f32 v[222:223], v[240:241], v[222:223]
	global_store_dwordx4 v[216:217], v[220:223], off
	s_nop 1
	v_cvt_pk_bf16_f32 v220, v220, v221
	v_cvt_pk_bf16_f32 v221, v222, v223
	global_store_dwordx2 v[214:215], v[220:221], off
	global_load_dwordx4 v[238:241], v[210:211], off
	v_lshlrev_b64 v[220:221], 11, v[246:247]
	v_lshl_add_u64 v[164:165], v[220:221], 0, v[164:165]
	v_lshlrev_b64 v[248:249], 2, v[164:165]
	v_lshl_add_u64 v[222:223], s[20:21], 0, v[250:251]
	v_lshl_add_u64 v[220:221], v[162:163], 0, v[128:129]
	v_lshl_add_u64 v[164:165], s[52:53], 0, v[248:249]
	v_lshl_add_u64 v[104:105], s[20:21], 0, v[248:249]
	s_waitcnt vmcnt(0) lgkmcnt(0)
	v_pk_add_f32 v[238:239], v[242:243], v[238:239]
	v_pk_add_f32 v[240:241], v[244:245], v[240:241]
	v_cvt_pk_bf16_f32 v162, v238, v239
	v_cvt_pk_bf16_f32 v163, v240, v241
	global_store_dwordx4 v[222:223], v[238:241], off
	global_store_dwordx2 v[220:221], v[162:163], off
	global_load_dwordx4 v[238:241], v[164:165], off
	v_mad_u64_u32 v[162:163], s[12:13], v148, s14, v[166:167]
	ds_read_b128 v[242:245], v162
	v_readlane_b32 s12, v254, 28
	s_add_i32 s16, s16, s12
	s_ashr_i32 s12, s16, 31
	s_lshr_b32 s12, s12, 27
	s_add_i32 s12, s16, s12
	s_ashr_i32 s12, s12, 5
	s_lshl_b32 s12, s12, 3
	v_readlane_b32 s13, v254, 24
	s_or_b32 s17, s12, s13
	s_cmp_gt_i32 s17, 31
	s_waitcnt vmcnt(0) lgkmcnt(0)
; __device__ __forceinline__ int accrow(int reg, int lh) { return (reg & 3) + 8 * (reg >> 2) + 4 * lh; }
; template <int EPI, int PN>
; __device__ void gemm_phase(const Params& p, const u16* __restrict__ A, const u16* __restrict__ Bt, int nNt, char* smem) {
;     ...
;     if (EPI == 1) {
; #pragma unroll
;       for (int j = 0; j < 2; ++j) {
; #pragma unroll
;         for (int i = 0; i < 4; ++i)
; #pragma unroll
;           for (int r = 0; r < 16; ++r) *(float*)(et + (i * 32 + accrow(r, lhE)) * 144 + lrE * 4) = acc[i][j][r];
; #pragma unroll
;         for (int it = 0; it < 16; ++it) {
;           const int c = it * 64 + laneE, row = c >> 3, seg = c & 7;
;           const float4 v = *(const float4*)(et + row * 144 + seg * 16);
;           const size_t g = (row0 + row) * DM + col0 + j * 32 + seg * 4;
;           const float4 xv = *(const float4*)(p.x + g);
;           const float4 hv = make_float4(xv.x + v.x, xv.y + v.y, xv.z + v.z, xv.w + v.w);
;           *(float4*)(p.out + g) = hv;
;           uint2 hb; hb.x = pack2(hv.x, hv.y); hb.y = pack2(hv.z, hv.w);
;           *(uint2*)(p.xn + (row0 + row) * LDK + col0 + j * 32 + seg * 4) = hb;
;         }
	v_pk_add_f32 v[238:239], v[242:243], v[238:239]
	v_pk_add_f32 v[240:241], v[244:245], v[240:241]
	v_cvt_pk_bf16_f32 v148, v238, v239
	v_cvt_pk_bf16_f32 v149, v240, v241
	global_store_dwordx4 v[104:105], v[238:241], off
	global_store_dwordx2 v[102:103], v[148:149], off
	global_load_dwordx4 v[238:241], v[160:161], off offset:128
	ds_write_b32 v159, v48
	ds_write_b32 v159, v49 offset:144
	ds_write_b32 v159, v50 offset:288
	ds_write_b32 v159, v51 offset:432
	ds_write_b32 v159, v52 offset:1152
	ds_write_b32 v159, v53 offset:1296
	ds_write_b32 v159, v54 offset:1440
	ds_write_b32 v159, v55 offset:1584
	ds_write_b32 v159, v56 offset:2304
	ds_write_b32 v159, v57 offset:2448
	ds_write_b32 v159, v58 offset:2592
	ds_write_b32 v159, v59 offset:2736
	ds_write_b32 v159, v60 offset:3456
	ds_write_b32 v159, v61 offset:3600
	ds_write_b32 v159, v62 offset:3744
	ds_write_b32 v159, v63 offset:3888
	ds_write_b32 v159, v32 offset:4608
	ds_write_b32 v159, v33 offset:4752
	ds_write_b32 v159, v34 offset:4896
	ds_write_b32 v159, v35 offset:5040
	ds_write_b32 v159, v36 offset:5760
	ds_write_b32 v159, v37 offset:5904
	ds_write_b32 v159, v38 offset:6048
	ds_write_b32 v159, v39 offset:6192
	ds_write_b32 v159, v40 offset:6912
	ds_write_b32 v159, v41 offset:7056
	ds_write_b32 v159, v42 offset:7200
	ds_write_b32 v159, v43 offset:7344
	ds_write_b32 v159, v44 offset:8064
	ds_write_b32 v159, v45 offset:8208
	ds_write_b32 v159, v46 offset:8352
	ds_write_b32 v159, v47 offset:8496
	ds_write_b32 v159, v16 offset:9216
	ds_write_b32 v159, v17 offset:9360
	ds_write_b32 v159, v18 offset:9504
	ds_write_b32 v159, v19 offset:9648
	ds_write_b32 v159, v20 offset:10368
	ds_write_b32 v159, v21 offset:10512
	ds_write_b32 v159, v22 offset:10656
	ds_write_b32 v159, v23 offset:10800
	ds_write_b32 v159, v24 offset:11520
	ds_write_b32 v159, v25 offset:11664
	ds_write_b32 v159, v26 offset:11808
	ds_write_b32 v159, v27 offset:11952
	ds_write_b32 v159, v28 offset:12672
	ds_write_b32 v159, v29 offset:12816
	ds_write_b32 v159, v30 offset:12960
	ds_write_b32 v159, v31 offset:13104
	ds_write_b32 v159, v0 offset:13824
	ds_write_b32 v159, v1 offset:13968
	ds_write_b32 v159, v2 offset:14112
	ds_write_b32 v159, v3 offset:14256
	ds_write_b32 v159, v4 offset:14976
	ds_write_b32 v159, v5 offset:15120
	ds_write_b32 v159, v6 offset:15264
	ds_write_b32 v159, v7 offset:15408
	ds_write_b32 v159, v8 offset:16128
	ds_write_b32 v159, v9 offset:16272
	ds_write_b32 v159, v10 offset:16416
	ds_write_b32 v159, v11 offset:16560
	ds_write_b32 v159, v12 offset:17280
	ds_write_b32 v159, v13 offset:17424
	ds_write_b32 v159, v14 offset:17568
	ds_write_b32 v159, v15 offset:17712
	ds_read_b128 v[0:3], v158
	ds_read_b128 v[4:7], v72
	s_waitcnt vmcnt(0) lgkmcnt(1)
	v_pk_add_f32 v[0:1], v[0:1], v[238:239]
	v_pk_add_f32 v[2:3], v[2:3], v[240:241]
	global_store_dwordx4 v[64:65], v[0:3], off offset:128
	s_nop 1
	v_cvt_pk_bf16_f32 v0, v0, v1
	v_cvt_pk_bf16_f32 v1, v2, v3
	global_store_dwordx2 v[66:67], v[0:1], off offset:64
	global_load_dwordx4 v[0:3], v[68:69], off offset:128
	s_waitcnt vmcnt(0) lgkmcnt(0)
	v_pk_add_f32 v[0:1], v[4:5], v[0:1]
	v_pk_add_f32 v[2:3], v[6:7], v[2:3]
	global_store_dwordx4 v[76:77], v[0:3], off offset:128
	ds_read_b128 v[4:7], v80
	s_nop 0
	v_cvt_pk_bf16_f32 v0, v0, v1
	v_cvt_pk_bf16_f32 v1, v2, v3
	global_store_dwordx2 v[74:75], v[0:1], off offset:64
	global_load_dwordx4 v[0:3], v[70:71], off offset:128
	s_waitcnt vmcnt(0) lgkmcnt(0)
	v_pk_add_f32 v[0:1], v[4:5], v[0:1]
	v_pk_add_f32 v[2:3], v[6:7], v[2:3]
	global_store_dwordx4 v[84:85], v[0:3], off offset:128
	ds_read_b128 v[4:7], v88
	s_nop 0
	v_cvt_pk_bf16_f32 v0, v0, v1
	v_cvt_pk_bf16_f32 v1, v2, v3
	global_store_dwordx2 v[82:83], v[0:1], off offset:64
	global_load_dwordx4 v[0:3], v[78:79], off offset:128
	s_waitcnt vmcnt(0) lgkmcnt(0)
	v_pk_add_f32 v[0:1], v[4:5], v[0:1]
	v_pk_add_f32 v[2:3], v[6:7], v[2:3]
	global_store_dwordx4 v[92:93], v[0:3], off offset:128
	ds_read_b128 v[4:7], v96
	s_nop 0
	v_cvt_pk_bf16_f32 v0, v0, v1
	v_cvt_pk_bf16_f32 v1, v2, v3
	global_store_dwordx2 v[90:91], v[0:1], off offset:64
	global_load_dwordx4 v[0:3], v[86:87], off offset:128
	s_waitcnt vmcnt(0) lgkmcnt(0)
; template <int EPI, int PN>
; __device__ void gemm_phase(const Params& p, const u16* __restrict__ A, const u16* __restrict__ Bt, int nNt, char* smem) {
;     ...
; #pragma unroll
;         for (int it = 0; it < 16; ++it) {
;           const int c = it * 64 + laneE, row = c >> 3, seg = c & 7;
;           const float4 v = *(const float4*)(et + row * 144 + seg * 16);
;           const size_t g = (row0 + row) * DM + col0 + j * 32 + seg * 4;
;           const float4 xv = *(const float4*)(p.x + g);
;           const float4 hv = make_float4(xv.x + v.x, xv.y + v.y, xv.z + v.z, xv.w + v.w);
;           *(float4*)(p.out + g) = hv;
;           uint2 hb; hb.x = pack2(hv.x, hv.y); hb.y = pack2(hv.z, hv.w);
;           *(uint2*)(p.xn + (row0 + row) * LDK + col0 + j * 32 + seg * 4) = hb;
;         }
;     ...
;     __syncthreads();
;   }
	v_pk_add_f32 v[0:1], v[4:5], v[0:1]
	v_pk_add_f32 v[2:3], v[6:7], v[2:3]
	global_store_dwordx4 v[100:101], v[0:3], off offset:128
	ds_read_b128 v[4:7], v108
	s_nop 0
	v_cvt_pk_bf16_f32 v0, v0, v1
	v_cvt_pk_bf16_f32 v1, v2, v3
	global_store_dwordx2 v[98:99], v[0:1], off offset:64
	global_load_dwordx4 v[0:3], v[94:95], off offset:128
	s_waitcnt vmcnt(0) lgkmcnt(0)
	v_pk_add_f32 v[0:1], v[4:5], v[0:1]
	v_pk_add_f32 v[2:3], v[6:7], v[2:3]
	global_store_dwordx4 v[112:113], v[0:3], off offset:128
	ds_read_b128 v[4:7], v116
	s_nop 0
	v_cvt_pk_bf16_f32 v0, v0, v1
	v_cvt_pk_bf16_f32 v1, v2, v3
	global_store_dwordx2 v[110:111], v[0:1], off offset:64
	global_load_dwordx4 v[0:3], v[106:107], off offset:128
	s_waitcnt vmcnt(0) lgkmcnt(0)
	v_pk_add_f32 v[0:1], v[4:5], v[0:1]
	v_pk_add_f32 v[2:3], v[6:7], v[2:3]
	global_store_dwordx4 v[120:121], v[0:3], off offset:128
	ds_read_b128 v[4:7], v124
	s_nop 0
	v_cvt_pk_bf16_f32 v0, v0, v1
	v_cvt_pk_bf16_f32 v1, v2, v3
	global_store_dwordx2 v[118:119], v[0:1], off offset:64
	global_load_dwordx4 v[0:3], v[114:115], off offset:128
	s_waitcnt vmcnt(0) lgkmcnt(0)
	v_pk_add_f32 v[0:1], v[4:5], v[0:1]
	v_pk_add_f32 v[2:3], v[6:7], v[2:3]
	global_store_dwordx4 v[168:169], v[0:3], off offset:128
	ds_read_b128 v[4:7], v172
	s_nop 0
	v_cvt_pk_bf16_f32 v0, v0, v1
	v_cvt_pk_bf16_f32 v1, v2, v3
	global_store_dwordx2 v[126:127], v[0:1], off offset:64
	global_load_dwordx4 v[0:3], v[122:123], off offset:128
	s_waitcnt vmcnt(0) lgkmcnt(0)
	v_pk_add_f32 v[0:1], v[4:5], v[0:1]
	v_pk_add_f32 v[2:3], v[6:7], v[2:3]
	global_store_dwordx4 v[176:177], v[0:3], off offset:128
	ds_read_b128 v[4:7], v180
	s_nop 0
	v_cvt_pk_bf16_f32 v0, v0, v1
	v_cvt_pk_bf16_f32 v1, v2, v3
	global_store_dwordx2 v[174:175], v[0:1], off offset:64
	global_load_dwordx4 v[0:3], v[170:171], off offset:128
	s_waitcnt vmcnt(0) lgkmcnt(0)
	v_pk_add_f32 v[0:1], v[4:5], v[0:1]
	v_pk_add_f32 v[2:3], v[6:7], v[2:3]
	global_store_dwordx4 v[184:185], v[0:3], off offset:128
	ds_read_b128 v[4:7], v188
	s_nop 0
	v_cvt_pk_bf16_f32 v0, v0, v1
	v_cvt_pk_bf16_f32 v1, v2, v3
	global_store_dwordx2 v[182:183], v[0:1], off offset:64
	global_load_dwordx4 v[0:3], v[178:179], off offset:128
	s_waitcnt vmcnt(0) lgkmcnt(0)
	v_pk_add_f32 v[0:1], v[4:5], v[0:1]
	v_pk_add_f32 v[2:3], v[6:7], v[2:3]
	global_store_dwordx4 v[192:193], v[0:3], off offset:128
	ds_read_b128 v[4:7], v196
	s_nop 0
	v_cvt_pk_bf16_f32 v0, v0, v1
	v_cvt_pk_bf16_f32 v1, v2, v3
	global_store_dwordx2 v[190:191], v[0:1], off offset:64
	global_load_dwordx4 v[0:3], v[186:187], off offset:128
	s_waitcnt vmcnt(0) lgkmcnt(0)
	v_pk_add_f32 v[0:1], v[4:5], v[0:1]
	v_pk_add_f32 v[2:3], v[6:7], v[2:3]
	global_store_dwordx4 v[200:201], v[0:3], off offset:128
	ds_read_b128 v[4:7], v204
	s_nop 0
	v_cvt_pk_bf16_f32 v0, v0, v1
	v_cvt_pk_bf16_f32 v1, v2, v3
	global_store_dwordx2 v[198:199], v[0:1], off offset:64
	global_load_dwordx4 v[0:3], v[194:195], off offset:128
	s_waitcnt vmcnt(0) lgkmcnt(0)
	v_pk_add_f32 v[0:1], v[4:5], v[0:1]
	v_pk_add_f32 v[2:3], v[6:7], v[2:3]
	global_store_dwordx4 v[208:209], v[0:3], off offset:128
	ds_read_b128 v[4:7], v212
	s_nop 0
	v_cvt_pk_bf16_f32 v0, v0, v1
	v_cvt_pk_bf16_f32 v1, v2, v3
	global_store_dwordx2 v[206:207], v[0:1], off offset:64
	global_load_dwordx4 v[0:3], v[202:203], off offset:128
	s_waitcnt vmcnt(0) lgkmcnt(0)
	v_pk_add_f32 v[0:1], v[4:5], v[0:1]
	v_pk_add_f32 v[2:3], v[6:7], v[2:3]
	global_store_dwordx4 v[216:217], v[0:3], off offset:128
	ds_read_b128 v[4:7], v218
	s_nop 0
	v_cvt_pk_bf16_f32 v0, v0, v1
	v_cvt_pk_bf16_f32 v1, v2, v3
	global_store_dwordx2 v[214:215], v[0:1], off offset:64
	global_load_dwordx4 v[0:3], v[210:211], off offset:128
	s_waitcnt vmcnt(0) lgkmcnt(0)
	v_pk_add_f32 v[0:1], v[4:5], v[0:1]
	v_pk_add_f32 v[2:3], v[6:7], v[2:3]
	global_store_dwordx4 v[222:223], v[0:3], off offset:128
	ds_read_b128 v[4:7], v162
	s_nop 0
	v_cvt_pk_bf16_f32 v0, v0, v1
	v_cvt_pk_bf16_f32 v1, v2, v3
	global_store_dwordx2 v[220:221], v[0:1], off offset:64
	global_load_dwordx4 v[0:3], v[164:165], off offset:128
	s_waitcnt vmcnt(0) lgkmcnt(0)
	v_pk_add_f32 v[0:1], v[4:5], v[0:1]
	v_pk_add_f32 v[2:3], v[6:7], v[2:3]
	global_store_dwordx4 v[104:105], v[0:3], off offset:128
	s_nop 1
	v_cvt_pk_bf16_f32 v0, v0, v1
	v_cvt_pk_bf16_f32 v1, v2, v3
	global_store_dwordx2 v[102:103], v[0:1], off offset:64
	s_barrier
	s_cbranch_scc0 .LBB0_665

; template <int EPI, int PN>
; __device__ void gemm_phase(const Params& p, const u16* __restrict__ A, const u16* __restrict__ Bt, int nNt, char* smem) {
;     ...
;     for (int kt = 0; kt < 32; ++kt) {
;       asm volatile("s_waitcnt vmcnt(0)" ::: "memory");
;       __builtin_amdgcn_s_barrier();
;       const u16* Ab = ring + (kt & 1) * STG;
;       const u16* Bb = Ab + 16384;
;       u16* st = ring + ((kt + 1) & 1) * STG;
;       const bool pre = (kt + 1 < 32);
;       s16x8 af[2][4], bf[2][2];
;       auto ldfrag = [&](int ks, int slot) {
; #pragma unroll
;         for (int i = 0; i < 4; ++i) {
;           const int row = wr * 128 + i * 32 + lr;
;           af[slot][i] = *(const s16x8*)(Ab + row * 64 + (((ks * 2 + lh) ^ ((row >> 1) & 7)) * 8));
;         }
; #pragma unroll
;         for (int j = 0; j < 2; ++j) {
;           const int rowb = nh * 128 + wc * 64 + j * 32 + lr;
;           bf[slot][j] = *(const s16x8*)(Bb + rowb * 64 + (((ks * 2 + lh) ^ ((rowb >> 1) & 7)) * 8));
;         }
;       };
;       ldfrag(0, 0);
;       ldfrag(1, 1);
;       __builtin_amdgcn_sched_barrier(0);
; #pragma unroll
;       for (int ks = 0; ks < 4; ++ks) {
;         const int slot = ks & 1;
; #pragma unroll
;         for (int i = 0; i < 4; ++i) {
;           acc[i][0] = mfma32(af[slot][i], bf[slot][0], acc[i][0]);
;           acc[i][1] = mfma32(af[slot][i], bf[slot][1], acc[i][1]);
;           __builtin_amdgcn_sched_barrier(0);
;           if (pre && (i & 1) == 0) {
;             const int pi = ks * 2 + (i >> 1);
;             if (pi < 4) glds16(Ag0 + (size_t)pi * 64 * LDK + (kt + 1) * 64, st + (srow + 64 * pi) * 64 + sch * 8);
;             else glds16(Bg0 + (size_t)(pi - 4) * 64 * LDK + (kt + 1) * 64, st + 16384 + (srow + 64 * (pi - 4)) * 64 + sch * 8);
;             __builtin_amdgcn_sched_barrier(0);
;           }
;         }
;         if (ks + 2 < 4) { ldfrag(ks + 2, slot); __builtin_amdgcn_sched_barrier(0); }
;       }
.Lrot723_loop:
	s_add_i32 s15, s11, 0xffff8000
	s_and_b32 s15, s15, 0x8000
	s_lshl_b32 s15, s15, 1
	v_lshl_or_b32 v128, v143, 1, s15
	v_lshl_add_u32 v149, v147, 1, s15
	s_and_b32 s98, s11, 0x8000
	s_lshl_b32 s98, s98, 1
	s_waitcnt lgkmcnt(7)
	v_mfma_f32_32x32x16_bf16 v[112:127], v[178:181], v[194:197], v[112:127]
	v_add3_u32 v226, s98, v162, v156
	s_waitcnt lgkmcnt(6)
	v_mfma_f32_32x32x16_bf16 v[96:111], v[178:181], v[198:201], v[96:111]
	v_readfirstlane_b32 s100, v226
	s_mov_b32 s16, m0
	s_add_i32 m0, s100, 0x8000
	s_nop 0
	global_load_lds_dwordx4 v[160:161], off
	v_mfma_f32_32x32x16_bf16 v[80:95], v[182:185], v[194:197], v[80:95]
	v_lshl_add_u64 v[178:179], v[160:161], 0, s[2:3]
	s_add_i32 m0, s100, 0xa000
	s_nop 0
	global_load_lds_dwordx4 v[178:179], off
	v_mfma_f32_32x32x16_bf16 v[64:79], v[182:185], v[198:201], v[64:79]
	v_lshl_add_u64 v[180:181], v[160:161], 0, s[4:5]
	s_add_i32 m0, s100, 0xc000
	s_nop 0
	global_load_lds_dwordx4 v[180:181], off
	v_mfma_f32_32x32x16_bf16 v[48:63], v[186:189], v[194:197], v[48:63]
	v_lshl_add_u64 v[178:179], v[160:161], 0, s[6:7]
	s_add_i32 m0, s100, 0xe000
	s_nop 0
	global_load_lds_dwordx4 v[178:179], off
	s_mov_b32 m0, s16
	v_mfma_f32_32x32x16_bf16 v[32:47], v[186:189], v[198:201], v[32:47]
	v_mfma_f32_32x32x16_bf16 v[16:31], v[190:193], v[194:197], v[16:31]
	v_mfma_f32_32x32x16_bf16 v[0:15], v[190:193], v[198:201], v[0:15]
	v_lshl_add_u64 v[160:161], v[160:161], 0, s[8:9]
	v_add_u32_e32 v177, v128, v175
	ds_read_b128 v[178:181], v177
	ds_read_b128 v[182:185], v177 offset:4096
	ds_read_b128 v[186:189], v177 offset:8192
	ds_read_b128 v[190:193], v177 offset:12288
	v_add_u32_e32 v177, v149, v175
	ds_read_b128 v[194:197], v177 offset:32768
	ds_read_b128 v[198:201], v177 offset:36864
	s_waitcnt lgkmcnt(7)
	v_mfma_f32_32x32x16_bf16 v[112:127], v[202:205], v[218:221], v[112:127]
	s_waitcnt lgkmcnt(6)
	v_mfma_f32_32x32x16_bf16 v[96:111], v[202:205], v[222:225], v[96:111]
	v_mfma_f32_32x32x16_bf16 v[80:95], v[206:209], v[218:221], v[80:95]
	v_mfma_f32_32x32x16_bf16 v[64:79], v[206:209], v[222:225], v[64:79]
	v_mfma_f32_32x32x16_bf16 v[48:63], v[210:213], v[218:221], v[48:63]
	v_mfma_f32_32x32x16_bf16 v[32:47], v[210:213], v[222:225], v[32:47]
	v_mfma_f32_32x32x16_bf16 v[16:31], v[214:217], v[218:221], v[16:31]
	v_mfma_f32_32x32x16_bf16 v[0:15], v[214:217], v[222:225], v[0:15]
	v_add_u32_e32 v128, v128, v176
	ds_read_b128 v[202:205], v128
	ds_read_b128 v[206:209], v128 offset:4096
	ds_read_b128 v[210:213], v128 offset:8192
	ds_read_b128 v[214:217], v128 offset:12288
	v_add_u32_e32 v128, v149, v176
	ds_read_b128 v[218:221], v128 offset:32768
	ds_read_b128 v[222:225], v128 offset:36864
	s_waitcnt lgkmcnt(7)
	v_mfma_f32_32x32x16_bf16 v[112:127], v[178:181], v[194:197], v[112:127]
	s_waitcnt lgkmcnt(6)
	v_mfma_f32_32x32x16_bf16 v[96:111], v[178:181], v[198:201], v[96:111]
	v_mfma_f32_32x32x16_bf16 v[80:95], v[182:185], v[194:197], v[80:95]
	v_mfma_f32_32x32x16_bf16 v[64:79], v[182:185], v[198:201], v[64:79]
	v_mfma_f32_32x32x16_bf16 v[48:63], v[186:189], v[194:197], v[48:63]
	v_mfma_f32_32x32x16_bf16 v[32:47], v[186:189], v[198:201], v[32:47]
	v_mfma_f32_32x32x16_bf16 v[16:31], v[190:193], v[194:197], v[16:31]
	v_mfma_f32_32x32x16_bf16 v[0:15], v[190:193], v[198:201], v[0:15]
	v_lshl_or_b32 v227, v143, 1, s98
	v_lshl_add_u32 v229, v147, 1, s98
	v_add_u32_e32 v228, v227, v173
	v_add_u32_e32 v230, v229, v173
	s_waitcnt vmcnt(0) lgkmcnt(0)
	s_barrier
	ds_read_b128 v[178:181], v228
	ds_read_b128 v[182:185], v228 offset:4096
	ds_read_b128 v[186:189], v228 offset:8192
	ds_read_b128 v[190:193], v228 offset:12288
	ds_read_b128 v[194:197], v230 offset:32768
	ds_read_b128 v[198:201], v230 offset:36864
	v_add3_u32 v226, s15, v162, v156
	v_mfma_f32_32x32x16_bf16 v[112:127], v[202:205], v[218:221], v[112:127]
	v_readfirstlane_b32 s99, v226
	s_mov_b32 s16, m0
	s_mov_b32 m0, s99
	s_nop 0
	global_load_lds_dwordx4 v[158:159], off
	v_mfma_f32_32x32x16_bf16 v[96:111], v[202:205], v[222:225], v[96:111]
	v_lshl_add_u64 v[232:233], v[158:159], 0, s[2:3]
	s_add_i32 m0, s99, 0x2000
	s_nop 0
	global_load_lds_dwordx4 v[232:233], off
	v_mfma_f32_32x32x16_bf16 v[80:95], v[206:209], v[218:221], v[80:95]
	v_lshl_add_u64 v[234:235], v[158:159], 0, s[4:5]
	s_add_i32 m0, s99, 0x4000
	s_nop 0
	global_load_lds_dwordx4 v[234:235], off
	v_mfma_f32_32x32x16_bf16 v[64:79], v[206:209], v[222:225], v[64:79]
	v_lshl_add_u64 v[232:233], v[158:159], 0, s[6:7]
	s_add_i32 m0, s99, 0x6000
	s_nop 0
	global_load_lds_dwordx4 v[232:233], off
	s_mov_b32 m0, s16
	v_mfma_f32_32x32x16_bf16 v[48:63], v[210:213], v[218:221], v[48:63]
	v_mfma_f32_32x32x16_bf16 v[32:47], v[210:213], v[222:225], v[32:47]
	v_mfma_f32_32x32x16_bf16 v[16:31], v[214:217], v[218:221], v[16:31]
	v_mfma_f32_32x32x16_bf16 v[0:15], v[214:217], v[222:225], v[0:15]
	v_add_u32_e32 v228, v227, v174
	v_add_u32_e32 v230, v229, v174
	ds_read_b128 v[202:205], v228
	ds_read_b128 v[206:209], v228 offset:4096
	ds_read_b128 v[210:213], v228 offset:8192
	ds_read_b128 v[214:217], v228 offset:12288
	ds_read_b128 v[218:221], v230 offset:32768
	ds_read_b128 v[222:225], v230 offset:36864
	s_add_i32 s11, s11, 0x8000
	v_lshl_add_u64 v[158:159], v[158:159], 0, s[8:9]
	s_cmp_eq_u32 s11, 0xf8000
	s_cbranch_scc0 .Lrot723_loop
; template <int EPI, int PN>
; __device__ void gemm_phase(const Params& p, const u16* __restrict__ A, const u16* __restrict__ Bt, int nNt, char* smem) {
;     ...
;     for (int kt = 0; kt < 32; ++kt) {
;       asm volatile("s_waitcnt vmcnt(0)" ::: "memory");
;       __builtin_amdgcn_s_barrier();
;       const u16* Ab = ring + (kt & 1) * STG;
;       const u16* Bb = Ab + 16384;
;       u16* st = ring + ((kt + 1) & 1) * STG;
;       const bool pre = (kt + 1 < 32);
;       s16x8 af[2][4], bf[2][2];
;       auto ldfrag = [&](int ks, int slot) {
; #pragma unroll
;         for (int i = 0; i < 4; ++i) {
;           const int row = wr * 128 + i * 32 + lr;
;           af[slot][i] = *(const s16x8*)(Ab + row * 64 + (((ks * 2 + lh) ^ ((row >> 1) & 7)) * 8));
;         }
; #pragma unroll
;         for (int j = 0; j < 2; ++j) {
;           const int rowb = nh * 128 + wc * 64 + j * 32 + lr;
;           bf[slot][j] = *(const s16x8*)(Bb + rowb * 64 + (((ks * 2 + lh) ^ ((rowb >> 1) & 7)) * 8));
;         }
;       };
;       ldfrag(0, 0);
;       ldfrag(1, 1);
;       __builtin_amdgcn_sched_barrier(0);
; #pragma unroll
;       for (int ks = 0; ks < 4; ++ks) {
;         const int slot = ks & 1;
; #pragma unroll
;         for (int i = 0; i < 4; ++i) {
;           acc[i][0] = mfma32(af[slot][i], bf[slot][0], acc[i][0]);
;           acc[i][1] = mfma32(af[slot][i], bf[slot][1], acc[i][1]);
;           __builtin_amdgcn_sched_barrier(0);
;           if (pre && (i & 1) == 0) {
;             const int pi = ks * 2 + (i >> 1);
;             if (pi < 4) glds16(Ag0 + (size_t)pi * 64 * LDK + (kt + 1) * 64, st + (srow + 64 * pi) * 64 + sch * 8);
;             else glds16(Bg0 + (size_t)(pi - 4) * 64 * LDK + (kt + 1) * 64, st + 16384 + (srow + 64 * (pi - 4)) * 64 + sch * 8);
;             __builtin_amdgcn_sched_barrier(0);
;           }
;         }
;         if (ks + 2 < 4) { ldfrag(ks + 2, slot); __builtin_amdgcn_sched_barrier(0); }
;       }
	s_add_i32 s15, s11, 0xffff8000
	s_and_b32 s15, s15, 0x8000
	s_lshl_b32 s15, s15, 1
	v_lshl_or_b32 v128, v143, 1, s15
	v_lshl_add_u32 v149, v147, 1, s15
	s_and_b32 s98, s11, 0x8000
	s_lshl_b32 s98, s98, 1
	s_waitcnt lgkmcnt(7)
	v_mfma_f32_32x32x16_bf16 v[112:127], v[178:181], v[194:197], v[112:127]
	v_add3_u32 v226, s98, v162, v156
	s_waitcnt lgkmcnt(6)
	v_mfma_f32_32x32x16_bf16 v[96:111], v[178:181], v[198:201], v[96:111]
	v_readfirstlane_b32 s100, v226
	s_mov_b32 s16, m0
	s_add_i32 m0, s100, 0x8000
	s_nop 0
	global_load_lds_dwordx4 v[160:161], off
	v_mfma_f32_32x32x16_bf16 v[80:95], v[182:185], v[194:197], v[80:95]
	v_lshl_add_u64 v[178:179], v[160:161], 0, s[2:3]
	s_add_i32 m0, s100, 0xa000
	s_nop 0
	global_load_lds_dwordx4 v[178:179], off
	v_mfma_f32_32x32x16_bf16 v[64:79], v[182:185], v[198:201], v[64:79]
	v_lshl_add_u64 v[180:181], v[160:161], 0, s[4:5]
	s_add_i32 m0, s100, 0xc000
	s_nop 0
	global_load_lds_dwordx4 v[180:181], off
	v_mfma_f32_32x32x16_bf16 v[48:63], v[186:189], v[194:197], v[48:63]
	v_lshl_add_u64 v[178:179], v[160:161], 0, s[6:7]
	s_add_i32 m0, s100, 0xe000
	s_nop 0
	global_load_lds_dwordx4 v[178:179], off
	s_mov_b32 m0, s16
	v_mfma_f32_32x32x16_bf16 v[32:47], v[186:189], v[198:201], v[32:47]
	v_mfma_f32_32x32x16_bf16 v[16:31], v[190:193], v[194:197], v[16:31]
	v_mfma_f32_32x32x16_bf16 v[0:15], v[190:193], v[198:201], v[0:15]
	v_lshl_add_u64 v[160:161], v[160:161], 0, s[8:9]
	v_add_u32_e32 v177, v128, v175
	ds_read_b128 v[178:181], v177
	ds_read_b128 v[182:185], v177 offset:4096
	ds_read_b128 v[186:189], v177 offset:8192
	ds_read_b128 v[190:193], v177 offset:12288
	v_add_u32_e32 v177, v149, v175
	ds_read_b128 v[194:197], v177 offset:32768
	ds_read_b128 v[198:201], v177 offset:36864
	s_waitcnt lgkmcnt(7)
	v_mfma_f32_32x32x16_bf16 v[112:127], v[202:205], v[218:221], v[112:127]
	s_waitcnt lgkmcnt(6)
	v_mfma_f32_32x32x16_bf16 v[96:111], v[202:205], v[222:225], v[96:111]
	v_mfma_f32_32x32x16_bf16 v[80:95], v[206:209], v[218:221], v[80:95]
	v_mfma_f32_32x32x16_bf16 v[64:79], v[206:209], v[222:225], v[64:79]
	v_mfma_f32_32x32x16_bf16 v[48:63], v[210:213], v[218:221], v[48:63]
	v_mfma_f32_32x32x16_bf16 v[32:47], v[210:213], v[222:225], v[32:47]
	v_mfma_f32_32x32x16_bf16 v[16:31], v[214:217], v[218:221], v[16:31]
	v_mfma_f32_32x32x16_bf16 v[0:15], v[214:217], v[222:225], v[0:15]
	v_add_u32_e32 v128, v128, v176
	ds_read_b128 v[202:205], v128
	ds_read_b128 v[206:209], v128 offset:4096
	ds_read_b128 v[210:213], v128 offset:8192
	ds_read_b128 v[214:217], v128 offset:12288
	v_add_u32_e32 v128, v149, v176
	ds_read_b128 v[218:221], v128 offset:32768
	ds_read_b128 v[222:225], v128 offset:36864
	s_waitcnt lgkmcnt(7)
	v_mfma_f32_32x32x16_bf16 v[112:127], v[178:181], v[194:197], v[112:127]
	s_waitcnt lgkmcnt(6)
	v_mfma_f32_32x32x16_bf16 v[96:111], v[178:181], v[198:201], v[96:111]
	v_mfma_f32_32x32x16_bf16 v[80:95], v[182:185], v[194:197], v[80:95]
	v_mfma_f32_32x32x16_bf16 v[64:79], v[182:185], v[198:201], v[64:79]
	v_mfma_f32_32x32x16_bf16 v[48:63], v[186:189], v[194:197], v[48:63]
	v_mfma_f32_32x32x16_bf16 v[32:47], v[186:189], v[198:201], v[32:47]
	v_mfma_f32_32x32x16_bf16 v[16:31], v[190:193], v[194:197], v[16:31]
	v_mfma_f32_32x32x16_bf16 v[0:15], v[190:193], v[198:201], v[0:15]
	s_waitcnt lgkmcnt(1)
	v_mfma_f32_32x32x16_bf16 v[112:127], v[202:205], v[218:221], v[112:127]
	s_waitcnt lgkmcnt(0)
	v_mfma_f32_32x32x16_bf16 v[96:111], v[202:205], v[222:225], v[96:111]
	v_mfma_f32_32x32x16_bf16 v[80:95], v[206:209], v[218:221], v[80:95]
	v_mfma_f32_32x32x16_bf16 v[64:79], v[206:209], v[222:225], v[64:79]
	v_mfma_f32_32x32x16_bf16 v[48:63], v[210:213], v[218:221], v[48:63]
	v_mfma_f32_32x32x16_bf16 v[32:47], v[210:213], v[222:225], v[32:47]
	v_mfma_f32_32x32x16_bf16 v[16:31], v[214:217], v[218:221], v[16:31]
	v_mfma_f32_32x32x16_bf16 v[0:15], v[214:217], v[222:225], v[0:15]
	s_waitcnt vmcnt(0)
	s_barrier
	ds_read_b128 v[158:161], v164
	ds_read_b128 v[178:181], v164 offset:4096
	ds_read_b128 v[182:185], v164 offset:8192
	ds_read_b128 v[186:189], v164 offset:12288
	ds_read_b128 v[190:193], v165
	ds_read_b128 v[194:197], v165 offset:4096
	ds_read_b128 v[198:201], v166
	ds_read_b128 v[202:205], v166 offset:4096
	ds_read_b128 v[206:209], v166 offset:8192
	ds_read_b128 v[210:213], v166 offset:12288
	ds_read_b128 v[214:217], v168
	ds_read_b128 v[218:221], v168 offset:4096
	s_waitcnt lgkmcnt(7)
	v_mfma_f32_32x32x16_bf16 v[112:127], v[158:161], v[190:193], v[112:127]
	s_waitcnt lgkmcnt(6)
	v_mfma_f32_32x32x16_bf16 v[96:111], v[158:161], v[194:197], v[96:111]
	v_mfma_f32_32x32x16_bf16 v[80:95], v[178:181], v[190:193], v[80:95]
	v_mfma_f32_32x32x16_bf16 v[64:79], v[178:181], v[194:197], v[64:79]
	v_mfma_f32_32x32x16_bf16 v[48:63], v[182:185], v[190:193], v[48:63]
	v_mfma_f32_32x32x16_bf16 v[32:47], v[182:185], v[194:197], v[32:47]
	v_mfma_f32_32x32x16_bf16 v[16:31], v[186:189], v[190:193], v[16:31]
	v_mfma_f32_32x32x16_bf16 v[0:15], v[186:189], v[194:197], v[0:15]
	ds_read_b128 v[158:161], v169
	ds_read_b128 v[178:181], v169 offset:4096
	ds_read_b128 v[182:185], v169 offset:8192
	ds_read_b128 v[186:189], v169 offset:12288
	ds_read_b128 v[190:193], v170
	ds_read_b128 v[194:197], v170 offset:4096
	s_waitcnt lgkmcnt(7)
	v_mfma_f32_32x32x16_bf16 v[112:127], v[198:201], v[214:217], v[112:127]
	s_waitcnt lgkmcnt(6)
; __device__ __forceinline__ int accrow(int reg, int lh) { return (reg & 3) + 8 * (reg >> 2) + 4 * lh; }
; template <int EPI, int PN>
; __device__ void gemm_phase(const Params& p, const u16* __restrict__ A, const u16* __restrict__ Bt, int nNt, char* smem) {
;     ...
;     __syncthreads();
;     int mte = __builtin_amdgcn_readfirstlane(mt), nte = __builtin_amdgcn_readfirstlane(nt), lrE = lr, lhE = lh, laneE = lane;
;     asm volatile("" : "+s"(mte), "+s"(nte), "+v"(lrE), "+v"(lhE), "+v"(laneE));
;     unsigned char* et = (unsigned char*)smem + wv * 18432;
;     const int col0 = nte * 256 + nh * 128 + wc * 64;
;     const size_t row0 = (size_t)mte * 256 + wr * 128;
;     if (EPI == 1) {
; #pragma unroll
;       for (int j = 0; j < 2; ++j) {
; #pragma unroll
;         for (int i = 0; i < 4; ++i)
; #pragma unroll
;           for (int r = 0; r < 16; ++r) *(float*)(et + (i * 32 + accrow(r, lhE)) * 144 + lrE * 4) = acc[i][j][r];
; #pragma unroll
;         for (int it = 0; it < 16; ++it) {
;           const int c = it * 64 + laneE, row = c >> 3, seg = c & 7;
;           const float4 v = *(const float4*)(et + row * 144 + seg * 16);
;           const size_t g = (row0 + row) * DM + col0 + j * 32 + seg * 4;
;           const float4 xv = *(const float4*)(p.x + g);
;           const float4 hv = make_float4(xv.x + v.x, xv.y + v.y, xv.z + v.z, xv.w + v.w);
;           *(float4*)(p.out + g) = hv;
;           uint2 hb; hb.x = pack2(hv.x, hv.y); hb.y = pack2(hv.z, hv.w);
;           *(uint2*)(p.xn + (row0 + row) * LDK + col0 + j * 32 + seg * 4) = hb;
;         }
;       }
;     } else if (EPI == 0 && col0 >= NPROJ) {
; #pragma unroll
;       for (int i = 0; i < 4; ++i)
; #pragma unroll
;         for (int r = 0; r < 16; ++r) {
;           const size_t row = row0 + i * 32 + accrow(r, lhE);
;           const int col = col0 + lrE;
;           if (col < NIN) p.dtraw[row * 16 + (col - NPROJ)] = acc[i][0][r];
;         }
;     } else {
; #pragma unroll
;       for (int i = 0; i < 4; ++i)
; #pragma unroll
;         for (int j = 0; j < 2; ++j)
; #pragma unroll
;           for (int r = 0; r < 16; ++r) *(u16*)(et + (i * 32 + accrow(r, lhE)) * 144 + (j * 32 + lrE) * 2) = f2bf(acc[i][j][r]);
	v_mfma_f32_32x32x16_bf16 v[96:111], v[198:201], v[218:221], v[96:111]
	v_mfma_f32_32x32x16_bf16 v[80:95], v[202:205], v[214:217], v[80:95]
	v_mfma_f32_32x32x16_bf16 v[64:79], v[202:205], v[218:221], v[64:79]
	v_mfma_f32_32x32x16_bf16 v[48:63], v[206:209], v[214:217], v[48:63]
	v_mfma_f32_32x32x16_bf16 v[32:47], v[206:209], v[218:221], v[32:47]
	v_mfma_f32_32x32x16_bf16 v[16:31], v[210:213], v[214:217], v[16:31]
	v_mfma_f32_32x32x16_bf16 v[0:15], v[210:213], v[218:221], v[0:15]
	ds_read_b128 v[198:201], v171
	ds_read_b128 v[202:205], v171 offset:4096
	ds_read_b128 v[206:209], v171 offset:8192
	ds_read_b128 v[210:213], v171 offset:12288
	ds_read_b128 v[214:217], v172
	ds_read_b128 v[218:221], v172 offset:4096
	s_waitcnt lgkmcnt(7)
	v_mfma_f32_32x32x16_bf16 v[112:127], v[158:161], v[190:193], v[112:127]
	s_waitcnt lgkmcnt(6)
	v_mfma_f32_32x32x16_bf16 v[96:111], v[158:161], v[194:197], v[96:111]
	v_mfma_f32_32x32x16_bf16 v[80:95], v[178:181], v[190:193], v[80:95]
	v_mfma_f32_32x32x16_bf16 v[64:79], v[178:181], v[194:197], v[64:79]
	v_mfma_f32_32x32x16_bf16 v[48:63], v[182:185], v[190:193], v[48:63]
	v_mfma_f32_32x32x16_bf16 v[32:47], v[182:185], v[194:197], v[32:47]
	v_mfma_f32_32x32x16_bf16 v[16:31], v[186:189], v[190:193], v[16:31]
	v_mfma_f32_32x32x16_bf16 v[0:15], v[186:189], v[194:197], v[0:15]
	s_waitcnt lgkmcnt(1)
	v_mfma_f32_32x32x16_bf16 v[112:127], v[198:201], v[214:217], v[112:127]
	s_waitcnt lgkmcnt(0)
	v_mfma_f32_32x32x16_bf16 v[96:111], v[198:201], v[218:221], v[96:111]
	v_mfma_f32_32x32x16_bf16 v[80:95], v[202:205], v[214:217], v[80:95]
	v_mfma_f32_32x32x16_bf16 v[64:79], v[202:205], v[218:221], v[64:79]
	v_mfma_f32_32x32x16_bf16 v[48:63], v[206:209], v[214:217], v[48:63]
	v_mfma_f32_32x32x16_bf16 v[32:47], v[206:209], v[218:221], v[32:47]
	v_mfma_f32_32x32x16_bf16 v[16:31], v[210:213], v[214:217], v[16:31]
	v_mfma_f32_32x32x16_bf16 v[0:15], v[210:213], v[218:221], v[0:15]
	v_mov_b32_e32 v149, v135
	v_mov_b32_e32 v128, v139
	v_mov_b32_e32 v158, v137
	s_barrier
	s_nop 7
	v_cvt_pk_bf16_f32 v0, v0, s0
	v_lshlrev_b32_e32 v158, 1, v158
	v_mul_lo_u32 v128, v128, s12
	v_add3_u32 v128, v163, v158, v128
	v_cvt_pk_bf16_f32 v112, v112, s0
	v_cvt_pk_bf16_f32 v96, v96, s0
	v_cvt_pk_bf16_f32 v80, v80, s0
	v_cvt_pk_bf16_f32 v64, v64, s0
	v_cvt_pk_bf16_f32 v48, v48, s0
	v_cvt_pk_bf16_f32 v32, v32, s0
	v_cvt_pk_bf16_f32 v16, v16, s0
	ds_write_b16 v128, v0 offset:13888
	v_cvt_pk_bf16_f32 v0, v1, s0
	ds_write_b16 v128, v112
	v_cvt_pk_bf16_f32 v112, v113, s0
	ds_write_b16 v128, v96 offset:64
	v_cvt_pk_bf16_f32 v96, v97, s0
	ds_write_b16 v128, v80 offset:4608
	v_cvt_pk_bf16_f32 v80, v81, s0
	ds_write_b16 v128, v64 offset:4672
	v_cvt_pk_bf16_f32 v64, v65, s0
	ds_write_b16 v128, v48 offset:9216
	v_cvt_pk_bf16_f32 v48, v49, s0
	ds_write_b16 v128, v32 offset:9280
	v_cvt_pk_bf16_f32 v32, v33, s0
	ds_write_b16 v128, v16 offset:13824
	v_cvt_pk_bf16_f32 v16, v17, s0
	ds_write_b16 v128, v0 offset:14032
	v_cvt_pk_bf16_f32 v0, v2, s0
	ds_write_b16 v128, v112 offset:144
	v_cvt_pk_bf16_f32 v112, v114, s0
	ds_write_b16 v128, v96 offset:208
	v_cvt_pk_bf16_f32 v96, v98, s0
	ds_write_b16 v128, v80 offset:4752
	v_cvt_pk_bf16_f32 v80, v82, s0
	ds_write_b16 v128, v64 offset:4816
	v_cvt_pk_bf16_f32 v64, v66, s0
	ds_write_b16 v128, v48 offset:9360
	v_cvt_pk_bf16_f32 v48, v50, s0
	ds_write_b16 v128, v32 offset:9424
	v_cvt_pk_bf16_f32 v32, v34, s0
	ds_write_b16 v128, v16 offset:13968
	v_cvt_pk_bf16_f32 v16, v18, s0
	ds_write_b16 v128, v0 offset:14176
	v_cvt_pk_bf16_f32 v0, v3, s0
	ds_write_b16 v128, v112 offset:288
	v_cvt_pk_bf16_f32 v112, v115, s0
	ds_write_b16 v128, v96 offset:352
	v_cvt_pk_bf16_f32 v96, v99, s0
	ds_write_b16 v128, v80 offset:4896
	v_cvt_pk_bf16_f32 v80, v83, s0
	ds_write_b16 v128, v64 offset:4960
	v_cvt_pk_bf16_f32 v64, v67, s0
	ds_write_b16 v128, v48 offset:9504
	v_cvt_pk_bf16_f32 v48, v51, s0
	ds_write_b16 v128, v32 offset:9568
	v_cvt_pk_bf16_f32 v32, v35, s0
	ds_write_b16 v128, v16 offset:14112
	v_cvt_pk_bf16_f32 v16, v19, s0
	ds_write_b16 v128, v0 offset:14320
	v_cvt_pk_bf16_f32 v0, v4, s0
	ds_write_b16 v128, v112 offset:432
	v_cvt_pk_bf16_f32 v112, v116, s0
	ds_write_b16 v128, v96 offset:496
	v_cvt_pk_bf16_f32 v96, v100, s0
	ds_write_b16 v128, v80 offset:5040
	v_cvt_pk_bf16_f32 v80, v84, s0
	ds_write_b16 v128, v64 offset:5104
	v_cvt_pk_bf16_f32 v64, v68, s0
	ds_write_b16 v128, v48 offset:9648
	v_cvt_pk_bf16_f32 v48, v52, s0
	ds_write_b16 v128, v32 offset:9712
	v_cvt_pk_bf16_f32 v32, v36, s0
	ds_write_b16 v128, v16 offset:14256
	v_cvt_pk_bf16_f32 v16, v20, s0
	ds_write_b16 v128, v0 offset:15040
	v_cvt_pk_bf16_f32 v0, v5, s0
	ds_write_b16 v128, v112 offset:1152
	v_cvt_pk_bf16_f32 v112, v117, s0
	ds_write_b16 v128, v96 offset:1216
	v_cvt_pk_bf16_f32 v96, v101, s0
	ds_write_b16 v128, v80 offset:5760
	v_cvt_pk_bf16_f32 v80, v85, s0
	ds_write_b16 v128, v64 offset:5824
	v_cvt_pk_bf16_f32 v64, v69, s0
	ds_write_b16 v128, v48 offset:10368
	v_cvt_pk_bf16_f32 v48, v53, s0
	ds_write_b16 v128, v32 offset:10432
	v_cvt_pk_bf16_f32 v32, v37, s0
	ds_write_b16 v128, v16 offset:14976
	v_cvt_pk_bf16_f32 v16, v21, s0
	ds_write_b16 v128, v0 offset:15184
	v_cvt_pk_bf16_f32 v0, v6, s0
	ds_write_b16 v128, v112 offset:1296
	v_cvt_pk_bf16_f32 v112, v118, s0
	ds_write_b16 v128, v96 offset:1360
	v_cvt_pk_bf16_f32 v96, v102, s0
	ds_write_b16 v128, v80 offset:5904
	v_cvt_pk_bf16_f32 v80, v86, s0
	ds_write_b16 v128, v64 offset:5968
	v_cvt_pk_bf16_f32 v64, v70, s0
	ds_write_b16 v128, v48 offset:10512
	v_cvt_pk_bf16_f32 v48, v54, s0
	ds_write_b16 v128, v32 offset:10576
	v_cvt_pk_bf16_f32 v32, v38, s0
	ds_write_b16 v128, v16 offset:15120
	v_cvt_pk_bf16_f32 v16, v22, s0
; __device__ __forceinline__ int accrow(int reg, int lh) { return (reg & 3) + 8 * (reg >> 2) + 4 * lh; }
; template <int EPI, int PN>
; __device__ void gemm_phase(const Params& p, const u16* __restrict__ A, const u16* __restrict__ Bt, int nNt, char* smem) {
;     ...
;     } else {
; #pragma unroll
;       for (int i = 0; i < 4; ++i)
; #pragma unroll
;         for (int j = 0; j < 2; ++j)
; #pragma unroll
;           for (int r = 0; r < 16; ++r) *(u16*)(et + (i * 32 + accrow(r, lhE)) * 144 + (j * 32 + lrE) * 2) = f2bf(acc[i][j][r]);
; #pragma unroll
;       for (int it = 0; it < 16; ++it) {
;         const int c = it * 64 + laneE, row = c >> 3, seg = c & 7;
;         const uint4 v = *(const uint4*)(et + row * 144 + seg * 16);
;         if (EPI == 0) *(uint4*)(p.proj + (row0 + row) * NPROJ + col0 + seg * 8) = v;
;         else *(uint4*)(p.qp + (row0 + row) * DM + col0 + seg * 8) = v;
;       }
	ds_write_b16 v128, v0 offset:15328
	v_cvt_pk_bf16_f32 v0, v7, s0
	ds_write_b16 v128, v112 offset:1440
	v_cvt_pk_bf16_f32 v112, v119, s0
	ds_write_b16 v128, v96 offset:1504
	v_cvt_pk_bf16_f32 v96, v103, s0
	ds_write_b16 v128, v80 offset:6048
	v_cvt_pk_bf16_f32 v80, v87, s0
	ds_write_b16 v128, v64 offset:6112
	v_cvt_pk_bf16_f32 v64, v71, s0
	ds_write_b16 v128, v48 offset:10656
	v_cvt_pk_bf16_f32 v48, v55, s0
	ds_write_b16 v128, v32 offset:10720
	v_cvt_pk_bf16_f32 v32, v39, s0
	ds_write_b16 v128, v16 offset:15264
	v_cvt_pk_bf16_f32 v16, v23, s0
	ds_write_b16 v128, v0 offset:15472
	v_cvt_pk_bf16_f32 v0, v8, s0
	ds_write_b16 v128, v112 offset:1584
	v_cvt_pk_bf16_f32 v112, v120, s0
	ds_write_b16 v128, v96 offset:1648
	v_cvt_pk_bf16_f32 v96, v104, s0
	ds_write_b16 v128, v80 offset:6192
	v_cvt_pk_bf16_f32 v80, v88, s0
	ds_write_b16 v128, v64 offset:6256
	v_cvt_pk_bf16_f32 v64, v72, s0
	ds_write_b16 v128, v48 offset:10800
	v_cvt_pk_bf16_f32 v48, v56, s0
	ds_write_b16 v128, v32 offset:10864
	v_cvt_pk_bf16_f32 v32, v40, s0
	ds_write_b16 v128, v16 offset:15408
	v_cvt_pk_bf16_f32 v16, v24, s0
	ds_write_b16 v128, v0 offset:16192
	v_cvt_pk_bf16_f32 v0, v9, s0
	ds_write_b16 v128, v112 offset:2304
	v_cvt_pk_bf16_f32 v112, v121, s0
	ds_write_b16 v128, v96 offset:2368
	v_cvt_pk_bf16_f32 v96, v105, s0
	ds_write_b16 v128, v80 offset:6912
	v_cvt_pk_bf16_f32 v80, v89, s0
	ds_write_b16 v128, v64 offset:6976
	v_cvt_pk_bf16_f32 v64, v73, s0
	ds_write_b16 v128, v48 offset:11520
	v_cvt_pk_bf16_f32 v48, v57, s0
	ds_write_b16 v128, v32 offset:11584
	v_cvt_pk_bf16_f32 v32, v41, s0
	ds_write_b16 v128, v16 offset:16128
	v_cvt_pk_bf16_f32 v16, v25, s0
	ds_write_b16 v128, v0 offset:16336
	v_cvt_pk_bf16_f32 v0, v10, s0
	ds_write_b16 v128, v112 offset:2448
	v_cvt_pk_bf16_f32 v112, v122, s0
	ds_write_b16 v128, v96 offset:2512
	v_cvt_pk_bf16_f32 v96, v106, s0
	ds_write_b16 v128, v80 offset:7056
	v_cvt_pk_bf16_f32 v80, v90, s0
	ds_write_b16 v128, v64 offset:7120
	v_cvt_pk_bf16_f32 v64, v74, s0
	ds_write_b16 v128, v48 offset:11664
	v_cvt_pk_bf16_f32 v48, v58, s0
	ds_write_b16 v128, v32 offset:11728
	v_cvt_pk_bf16_f32 v32, v42, s0
	ds_write_b16 v128, v16 offset:16272
	v_cvt_pk_bf16_f32 v16, v26, s0
	ds_write_b16 v128, v0 offset:16480
	v_cvt_pk_bf16_f32 v0, v11, s0
	ds_write_b16 v128, v112 offset:2592
	v_cvt_pk_bf16_f32 v112, v123, s0
	ds_write_b16 v128, v96 offset:2656
	v_cvt_pk_bf16_f32 v96, v107, s0
	ds_write_b16 v128, v80 offset:7200
	v_cvt_pk_bf16_f32 v80, v91, s0
	ds_write_b16 v128, v64 offset:7264
	v_cvt_pk_bf16_f32 v64, v75, s0
	ds_write_b16 v128, v48 offset:11808
	v_cvt_pk_bf16_f32 v48, v59, s0
	ds_write_b16 v128, v32 offset:11872
	v_cvt_pk_bf16_f32 v32, v43, s0
	ds_write_b16 v128, v16 offset:16416
	v_cvt_pk_bf16_f32 v16, v27, s0
	ds_write_b16 v128, v0 offset:16624
	v_cvt_pk_bf16_f32 v0, v12, s0
	ds_write_b16 v128, v112 offset:2736
	v_cvt_pk_bf16_f32 v112, v124, s0
	ds_write_b16 v128, v96 offset:2800
	v_cvt_pk_bf16_f32 v96, v108, s0
	ds_write_b16 v128, v80 offset:7344
	v_cvt_pk_bf16_f32 v80, v92, s0
	ds_write_b16 v128, v64 offset:7408
	v_cvt_pk_bf16_f32 v64, v76, s0
	ds_write_b16 v128, v48 offset:11952
	v_cvt_pk_bf16_f32 v48, v60, s0
	ds_write_b16 v128, v32 offset:12016
	v_cvt_pk_bf16_f32 v32, v44, s0
	ds_write_b16 v128, v16 offset:16560
	v_cvt_pk_bf16_f32 v16, v28, s0
	ds_write_b16 v128, v0 offset:17344
	v_cvt_pk_bf16_f32 v0, v13, s0
	ds_write_b16 v128, v112 offset:3456
	v_cvt_pk_bf16_f32 v112, v125, s0
	ds_write_b16 v128, v96 offset:3520
	v_cvt_pk_bf16_f32 v96, v109, s0
	ds_write_b16 v128, v80 offset:8064
	v_cvt_pk_bf16_f32 v80, v93, s0
	ds_write_b16 v128, v64 offset:8128
	v_cvt_pk_bf16_f32 v64, v77, s0
	ds_write_b16 v128, v48 offset:12672
	v_cvt_pk_bf16_f32 v48, v61, s0
	ds_write_b16 v128, v32 offset:12736
	v_cvt_pk_bf16_f32 v32, v45, s0
	ds_write_b16 v128, v16 offset:17280
	v_cvt_pk_bf16_f32 v16, v29, s0
	ds_write_b16 v128, v0 offset:17488
	v_cvt_pk_bf16_f32 v0, v14, s0
	ds_write_b16 v128, v112 offset:3600
	v_cvt_pk_bf16_f32 v112, v126, s0
	ds_write_b16 v128, v96 offset:3664
	v_cvt_pk_bf16_f32 v96, v110, s0
	ds_write_b16 v128, v80 offset:8208
	v_cvt_pk_bf16_f32 v80, v94, s0
	ds_write_b16 v128, v64 offset:8272
	v_cvt_pk_bf16_f32 v64, v78, s0
	ds_write_b16 v128, v48 offset:12816
	v_cvt_pk_bf16_f32 v48, v62, s0
	ds_write_b16 v128, v32 offset:12880
	v_cvt_pk_bf16_f32 v32, v46, s0
	ds_write_b16 v128, v16 offset:17424
	v_cvt_pk_bf16_f32 v16, v30, s0
	ds_write_b16 v128, v0 offset:17632
	v_cvt_pk_bf16_f32 v0, v15, s0
	s_ashr_i32 s11, s10, 31
	ds_write_b16 v128, v112 offset:3744
	v_cvt_pk_bf16_f32 v112, v127, s0
	ds_write_b16 v128, v96 offset:3808
	v_cvt_pk_bf16_f32 v96, v111, s0
	ds_write_b16 v128, v80 offset:8352
	v_cvt_pk_bf16_f32 v80, v95, s0
	ds_write_b16 v128, v64 offset:8416
	v_cvt_pk_bf16_f32 v64, v79, s0
	ds_write_b16 v128, v48 offset:12960
	v_cvt_pk_bf16_f32 v48, v63, s0
	ds_write_b16 v128, v32 offset:13024
	v_cvt_pk_bf16_f32 v32, v47, s0
	ds_write_b16 v128, v16 offset:17568
	v_cvt_pk_bf16_f32 v16, v31, s0
	ds_write_b16 v128, v0 offset:17776
	v_lshlrev_b32_e32 v0, 4, v149
	s_lshl_b64 s[10:11], s[10:11], 8
	ds_write_b16 v128, v112 offset:3888
	ds_write_b16 v128, v96 offset:3952
	ds_write_b16 v128, v80 offset:8496
	ds_write_b16 v128, v64 offset:8560
	ds_write_b16 v128, v48 offset:13104
	ds_write_b16 v128, v32 offset:13168
	ds_write_b16 v128, v16 offset:17712
	v_and_b32_e32 v128, 0x70, v0
	v_ashrrev_i32_e32 v6, 3, v149
	v_mov_b32_e32 v9, s11
	v_or_b32_e32 v8, s10, v134
	v_add_u32_e32 v10, v163, v128
	v_ashrrev_i32_e32 v7, 31, v6
	v_lshl_add_u32 v4, s14, 8, v145
	v_mad_u64_u32 v[0:1], s[10:11], v6, s13, v[10:11]
	v_lshl_add_u64 v[6:7], v[8:9], 0, v[6:7]
	v_readlane_b32 s16, v253, 39
	v_ashrrev_i32_e32 v5, 31, v4
	v_lshlrev_b64 v[6:7], 12, v[6:7]
	v_readlane_b32 s26, v253, 49
	v_readlane_b32 s27, v253, 50
	ds_read_b128 v[0:3], v0
	v_lshlrev_b64 v[12:13], 1, v[4:5]
	v_lshl_add_u64 v[6:7], s[26:27], 0, v[6:7]
	v_lshl_add_u64 v[4:5], v[6:7], 0, v[12:13]
	v_lshl_add_u64 v[14:15], v[4:5], 0, v[128:129]
	v_add_u32_e32 v4, 64, v149
	v_ashrrev_i32_e32 v16, 3, v4
	v_mad_u64_u32 v[4:5], s[10:11], v16, s13, v[10:11]
	v_ashrrev_i32_e32 v17, 31, v16
	ds_read_b128 v[4:7], v4
	s_waitcnt lgkmcnt(1)
; template <int EPI, int PN>
; __device__ void gemm_phase(const Params& p, const u16* __restrict__ A, const u16* __restrict__ Bt, int nNt, char* smem) {
;     ...
; #pragma unroll
;       for (int it = 0; it < 16; ++it) {
;         const int c = it * 64 + laneE, row = c >> 3, seg = c & 7;
;         const uint4 v = *(const uint4*)(et + row * 144 + seg * 16);
;         if (EPI == 0) *(uint4*)(p.proj + (row0 + row) * NPROJ + col0 + seg * 8) = v;
;         else *(uint4*)(p.qp + (row0 + row) * DM + col0 + seg * 8) = v;
;       }
	global_store_dwordx4 v[14:15], v[0:3], off
	v_readlane_b32 s17, v253, 40
	v_readlane_b32 s18, v253, 41
	v_lshl_add_u64 v[0:1], v[8:9], 0, v[16:17]
	v_lshlrev_b64 v[0:1], 12, v[0:1]
	v_lshl_add_u64 v[0:1], s[26:27], 0, v[0:1]
	v_lshl_add_u64 v[0:1], v[0:1], 0, v[12:13]
	v_lshl_add_u64 v[0:1], v[0:1], 0, v[128:129]
	s_waitcnt lgkmcnt(0)
	global_store_dwordx4 v[0:1], v[4:7], off
	v_add_u32_e32 v0, 0x80, v149
	v_readlane_b32 s19, v253, 42
	v_ashrrev_i32_e32 v4, 3, v0
	v_ashrrev_i32_e32 v5, 31, v4
	v_mad_u64_u32 v[0:1], s[10:11], v4, s13, v[10:11]
	v_lshl_add_u64 v[4:5], v[8:9], 0, v[4:5]
	v_lshlrev_b64 v[4:5], 12, v[4:5]
	ds_read_b128 v[0:3], v0
	v_lshl_add_u64 v[4:5], s[26:27], 0, v[4:5]
	v_lshl_add_u64 v[4:5], v[4:5], 0, v[12:13]
	v_lshl_add_u64 v[14:15], v[4:5], 0, v[128:129]
	v_add_u32_e32 v4, 0xc0, v149
	v_ashrrev_i32_e32 v16, 3, v4
	v_mad_u64_u32 v[4:5], s[10:11], v16, s13, v[10:11]
	v_ashrrev_i32_e32 v17, 31, v16
	ds_read_b128 v[4:7], v4
	s_waitcnt lgkmcnt(1)
	global_store_dwordx4 v[14:15], v[0:3], off
	v_readlane_b32 s20, v253, 43
	v_readlane_b32 s21, v253, 44
	v_lshl_add_u64 v[0:1], v[8:9], 0, v[16:17]
	v_lshlrev_b64 v[0:1], 12, v[0:1]
	v_lshl_add_u64 v[0:1], s[26:27], 0, v[0:1]
	v_lshl_add_u64 v[0:1], v[0:1], 0, v[12:13]
	v_lshl_add_u64 v[0:1], v[0:1], 0, v[128:129]
	s_waitcnt lgkmcnt(0)
	global_store_dwordx4 v[0:1], v[4:7], off
	v_add_u32_e32 v0, 0x100, v149
	v_readlane_b32 s22, v253, 45
	v_ashrrev_i32_e32 v4, 3, v0
	v_ashrrev_i32_e32 v5, 31, v4
	v_mad_u64_u32 v[0:1], s[10:11], v4, s13, v[10:11]
	v_lshl_add_u64 v[4:5], v[8:9], 0, v[4:5]
	v_lshlrev_b64 v[4:5], 12, v[4:5]
	ds_read_b128 v[0:3], v0
	v_lshl_add_u64 v[4:5], s[26:27], 0, v[4:5]
	v_lshl_add_u64 v[4:5], v[4:5], 0, v[12:13]
	v_lshl_add_u64 v[14:15], v[4:5], 0, v[128:129]
	v_add_u32_e32 v4, 0x140, v149
	v_ashrrev_i32_e32 v16, 3, v4
	v_mad_u64_u32 v[4:5], s[10:11], v16, s13, v[10:11]
	v_ashrrev_i32_e32 v17, 31, v16
	ds_read_b128 v[4:7], v4
	s_waitcnt lgkmcnt(1)
	global_store_dwordx4 v[14:15], v[0:3], off
	v_readlane_b32 s23, v253, 46
	v_readlane_b32 s24, v253, 47
	v_lshl_add_u64 v[0:1], v[8:9], 0, v[16:17]
	v_lshlrev_b64 v[0:1], 12, v[0:1]
	v_lshl_add_u64 v[0:1], s[26:27], 0, v[0:1]
	v_lshl_add_u64 v[0:1], v[0:1], 0, v[12:13]
	v_lshl_add_u64 v[0:1], v[0:1], 0, v[128:129]
	s_waitcnt lgkmcnt(0)
	global_store_dwordx4 v[0:1], v[4:7], off
	v_add_u32_e32 v0, 0x180, v149
	v_readlane_b32 s25, v253, 48
	v_ashrrev_i32_e32 v4, 3, v0
	v_ashrrev_i32_e32 v5, 31, v4
	v_mad_u64_u32 v[0:1], s[10:11], v4, s13, v[10:11]
	v_lshl_add_u64 v[4:5], v[8:9], 0, v[4:5]
	v_lshlrev_b64 v[4:5], 12, v[4:5]
	ds_read_b128 v[0:3], v0
	v_lshl_add_u64 v[4:5], s[26:27], 0, v[4:5]
	v_lshl_add_u64 v[4:5], v[4:5], 0, v[12:13]
	v_lshl_add_u64 v[14:15], v[4:5], 0, v[128:129]
	v_add_u32_e32 v4, 0x1c0, v149
	v_ashrrev_i32_e32 v16, 3, v4
	v_mad_u64_u32 v[4:5], s[10:11], v16, s13, v[10:11]
	v_ashrrev_i32_e32 v17, 31, v16
	ds_read_b128 v[4:7], v4
	s_waitcnt lgkmcnt(1)
	global_store_dwordx4 v[14:15], v[0:3], off
	v_readlane_b32 s28, v253, 51
	v_readlane_b32 s29, v253, 52
	v_lshl_add_u64 v[0:1], v[8:9], 0, v[16:17]
	v_lshlrev_b64 v[0:1], 12, v[0:1]
	v_lshl_add_u64 v[0:1], s[26:27], 0, v[0:1]
	v_lshl_add_u64 v[0:1], v[0:1], 0, v[12:13]
	v_lshl_add_u64 v[0:1], v[0:1], 0, v[128:129]
	s_waitcnt lgkmcnt(0)
	global_store_dwordx4 v[0:1], v[4:7], off
	v_add_u32_e32 v0, 0x200, v149
	v_readlane_b32 s30, v253, 53
	v_ashrrev_i32_e32 v4, 3, v0
	v_ashrrev_i32_e32 v5, 31, v4
	v_mad_u64_u32 v[0:1], s[10:11], v4, s13, v[10:11]
	v_lshl_add_u64 v[4:5], v[8:9], 0, v[4:5]
	v_lshlrev_b64 v[4:5], 12, v[4:5]
	ds_read_b128 v[0:3], v0
	v_lshl_add_u64 v[4:5], s[26:27], 0, v[4:5]
	v_lshl_add_u64 v[4:5], v[4:5], 0, v[12:13]
	v_lshl_add_u64 v[14:15], v[4:5], 0, v[128:129]
	v_add_u32_e32 v4, 0x240, v149
	v_ashrrev_i32_e32 v16, 3, v4
	v_mad_u64_u32 v[4:5], s[10:11], v16, s13, v[10:11]
	v_ashrrev_i32_e32 v17, 31, v16
	ds_read_b128 v[4:7], v4
	s_waitcnt lgkmcnt(1)
; template <int EPI, int PN>
; __device__ void gemm_phase(const Params& p, const u16* __restrict__ A, const u16* __restrict__ Bt, int nNt, char* smem) {
;     ...
;   for (int q = jb;; q += NJ) {
;     const int pl = q / (4 * PN), w = q % (4 * PN);
;     const int gp = pl * 8 + xcd;
;     if (gp >= npatch) break;
;     ...
; #pragma unroll
;       for (int it = 0; it < 16; ++it) {
;         const int c = it * 64 + laneE, row = c >> 3, seg = c & 7;
;         const uint4 v = *(const uint4*)(et + row * 144 + seg * 16);
;         if (EPI == 0) *(uint4*)(p.proj + (row0 + row) * NPROJ + col0 + seg * 8) = v;
;         else *(uint4*)(p.qp + (row0 + row) * DM + col0 + seg * 8) = v;
;       }
;     }
;     __syncthreads();
;   }
	global_store_dwordx4 v[14:15], v[0:3], off
	v_readlane_b32 s31, v253, 54
	s_nop 0
	v_lshl_add_u64 v[0:1], v[8:9], 0, v[16:17]
	v_lshlrev_b64 v[0:1], 12, v[0:1]
	v_lshl_add_u64 v[0:1], s[26:27], 0, v[0:1]
	v_lshl_add_u64 v[0:1], v[0:1], 0, v[12:13]
	v_lshl_add_u64 v[0:1], v[0:1], 0, v[128:129]
	s_waitcnt lgkmcnt(0)
	global_store_dwordx4 v[0:1], v[4:7], off
	v_add_u32_e32 v0, 0x280, v149
	s_nop 0
	v_ashrrev_i32_e32 v4, 3, v0
	v_ashrrev_i32_e32 v5, 31, v4
	v_mad_u64_u32 v[0:1], s[10:11], v4, s13, v[10:11]
	v_lshl_add_u64 v[4:5], v[8:9], 0, v[4:5]
	v_lshlrev_b64 v[4:5], 12, v[4:5]
	ds_read_b128 v[0:3], v0
	v_lshl_add_u64 v[4:5], s[26:27], 0, v[4:5]
	v_lshl_add_u64 v[4:5], v[4:5], 0, v[12:13]
	v_lshl_add_u64 v[14:15], v[4:5], 0, v[128:129]
	v_add_u32_e32 v4, 0x2c0, v149
	v_ashrrev_i32_e32 v16, 3, v4
	v_mad_u64_u32 v[4:5], s[10:11], v16, s13, v[10:11]
	v_ashrrev_i32_e32 v17, 31, v16
	ds_read_b128 v[4:7], v4
	s_waitcnt lgkmcnt(1)
	global_store_dwordx4 v[14:15], v[0:3], off
	s_nop 1
	v_lshl_add_u64 v[0:1], v[8:9], 0, v[16:17]
	v_lshlrev_b64 v[0:1], 12, v[0:1]
	v_lshl_add_u64 v[0:1], s[26:27], 0, v[0:1]
	v_lshl_add_u64 v[0:1], v[0:1], 0, v[12:13]
	v_lshl_add_u64 v[0:1], v[0:1], 0, v[128:129]
	s_waitcnt lgkmcnt(0)
	global_store_dwordx4 v[0:1], v[4:7], off
	v_add_u32_e32 v0, 0x300, v149
	s_nop 0
	v_ashrrev_i32_e32 v4, 3, v0
	v_ashrrev_i32_e32 v5, 31, v4
	v_mad_u64_u32 v[0:1], s[10:11], v4, s13, v[10:11]
	v_lshl_add_u64 v[4:5], v[8:9], 0, v[4:5]
	v_lshlrev_b64 v[4:5], 12, v[4:5]
	ds_read_b128 v[0:3], v0
	v_lshl_add_u64 v[4:5], s[26:27], 0, v[4:5]
	v_lshl_add_u64 v[4:5], v[4:5], 0, v[12:13]
	v_lshl_add_u64 v[14:15], v[4:5], 0, v[128:129]
	v_add_u32_e32 v4, 0x340, v149
	v_ashrrev_i32_e32 v16, 3, v4
	v_mad_u64_u32 v[4:5], s[10:11], v16, s13, v[10:11]
	v_ashrrev_i32_e32 v17, 31, v16
	ds_read_b128 v[4:7], v4
	s_waitcnt lgkmcnt(1)
	global_store_dwordx4 v[14:15], v[0:3], off
	s_nop 1
	v_lshl_add_u64 v[0:1], v[8:9], 0, v[16:17]
	v_lshlrev_b64 v[0:1], 12, v[0:1]
	v_lshl_add_u64 v[0:1], s[26:27], 0, v[0:1]
	v_lshl_add_u64 v[0:1], v[0:1], 0, v[12:13]
	v_lshl_add_u64 v[0:1], v[0:1], 0, v[128:129]
	s_waitcnt lgkmcnt(0)
	global_store_dwordx4 v[0:1], v[4:7], off
	v_add_u32_e32 v0, 0x380, v149
	s_nop 0
	v_ashrrev_i32_e32 v4, 3, v0
	v_ashrrev_i32_e32 v5, 31, v4
	v_mad_u64_u32 v[0:1], s[10:11], v4, s13, v[10:11]
	v_lshl_add_u64 v[4:5], v[8:9], 0, v[4:5]
	v_lshlrev_b64 v[4:5], 12, v[4:5]
	v_lshl_add_u64 v[4:5], s[26:27], 0, v[4:5]
	v_lshl_add_u64 v[4:5], v[4:5], 0, v[12:13]
	v_lshl_add_u64 v[14:15], v[4:5], 0, v[128:129]
	v_add_u32_e32 v4, 0x3c0, v149
	v_ashrrev_i32_e32 v16, 3, v4
	ds_read_b128 v[0:3], v0
	v_mad_u64_u32 v[4:5], s[10:11], v16, s13, v[10:11]
	v_readlane_b32 s10, v254, 28
	s_add_i32 s34, s34, s10
	s_ashr_i32 s10, s34, 31
	v_ashrrev_i32_e32 v17, 31, v16
	s_lshr_b32 s10, s10, 27
	ds_read_b128 v[4:7], v4
	s_waitcnt lgkmcnt(1)
	global_store_dwordx4 v[14:15], v[0:3], off
	s_add_i32 s10, s34, s10
	s_ashr_i32 s10, s10, 5
	v_lshl_add_u64 v[0:1], v[8:9], 0, v[16:17]
	v_lshlrev_b64 v[0:1], 12, v[0:1]
	v_lshl_add_u64 v[0:1], s[26:27], 0, v[0:1]
	s_lshl_b32 s10, s10, 3
	v_readlane_b32 s11, v254, 24
	v_lshl_add_u64 v[0:1], v[0:1], 0, v[12:13]
	s_or_b32 s11, s10, s11
	v_lshl_add_u64 v[0:1], v[0:1], 0, v[128:129]
	s_cmp_gt_i32 s11, 31
	s_waitcnt lgkmcnt(0)
	global_store_dwordx4 v[0:1], v[4:7], off
	s_waitcnt vmcnt(63) expcnt(7) lgkmcnt(15)
	s_barrier
	s_cbranch_scc0 .LBB0_722
